# scan waves: y of two steps stored with one ds_write2_b64 (alternating accumulator pairs, no extra VALU)
# baseline (speedup 1.0000x reference)
.LBB0_390:
	s_and_b32 s3, s2, 1
	s_mul_i32 s8, s3, 0x5000
	v_add_u32_e32 v2, s8, v136
	s_mul_i32 s8, s2, 0xab
	s_bfe_u32 s8, s8, 0x70009
	s_mul_i32 s8, s8, 3
	s_sub_i32 s8, s2, s8
	s_and_b32 s8, s8, 0xff
	s_mulk_i32 s8, 0x1100
	v_add_u32_e32 v3, s8, v137
	v_lshl_add_u32 v1, s3, 12, v137
	v_add_u32_e32 v246, 0xd300, v1
	v_add_u32_e32 v247, 0xdb00, v1
	ds_read_b128 v[176:179], v2 offset:4096
	ds_read_b128 v[180:183], v2 offset:4112
	ds_read_b128 v[200:203], v2 offset:12288
	ds_read_b128 v[204:207], v2 offset:12304
	ds_read_b64 v[216:217], v3 offset:40960
	ds_read_b128 v[184:187], v2 offset:0
	ds_read_b128 v[188:191], v2 offset:16
	ds_read_b128 v[192:195], v2 offset:8192
	ds_read_b128 v[196:199], v2 offset:8208
	s_waitcnt lgkmcnt(0)
	v_pk_mul_f32 v[164:165], v[72:73], v[176:177]
	v_pk_mul_f32 v[166:167], v[80:81], v[176:177]
	ds_read_b128 v[208:211], v2 offset:16384
	v_pk_fma_f32 v[164:165], v[74:75], v[178:179], v[164:165]
	v_pk_fma_f32 v[166:167], v[82:83], v[178:179], v[166:167]
	ds_read_b128 v[212:215], v2 offset:16400
	v_pk_fma_f32 v[164:165], v[76:77], v[180:181], v[164:165]
	v_pk_fma_f32 v[166:167], v[84:85], v[180:181], v[166:167]
	ds_read_b128 v[4:7], v2 offset:4352
	v_pk_fma_f32 v[164:165], v[78:79], v[182:183], v[164:165]
	v_pk_fma_f32 v[166:167], v[86:87], v[182:183], v[166:167]
	ds_read_b128 v[8:11], v2 offset:4368
	v_pk_mul_f32 v[218:219], v[216:217], v[200:201] op_sel_hi:[0,1]
	v_pk_mul_f32 v[226:227], v[216:217], v[200:201] op_sel:[1,0]
	ds_read_b128 v[40:43], v2 offset:12544
	v_pk_mul_f32 v[220:221], v[216:217], v[202:203] op_sel_hi:[0,1]
	v_pk_mul_f32 v[228:229], v[216:217], v[202:203] op_sel:[1,0]
	ds_read_b128 v[44:47], v2 offset:12560
	v_pk_mul_f32 v[222:223], v[216:217], v[204:205] op_sel_hi:[0,1]
	v_pk_mul_f32 v[230:231], v[216:217], v[204:205] op_sel:[1,0]
	ds_read_b64 v[26:27], v3 offset:41216
	v_pk_mul_f32 v[224:225], v[216:217], v[206:207] op_sel_hi:[0,1]
	v_pk_mul_f32 v[234:235], v[216:217], v[206:207] op_sel:[1,0]
	ds_read_b128 v[12:15], v2 offset:256
	v_add_f32_e32 v172, v164, v165
	v_add_f32_e32 v174, v166, v167
	ds_read_b128 v[28:31], v2 offset:272
	v_pk_fma_f32 v[218:219], v[72:73], v[184:185], v[218:219]
	v_pk_fma_f32 v[226:227], v[80:81], v[184:185], v[226:227]
	ds_read_b128 v[32:35], v2 offset:8448
	v_pk_fma_f32 v[220:221], v[74:75], v[186:187], v[220:221]
	v_pk_fma_f32 v[228:229], v[82:83], v[186:187], v[228:229]
	ds_read_b128 v[36:39], v2 offset:8464
	v_add_f32_dpp v172, v172, v172 quad_perm:[1,0,3,2] row_mask:0xf bank_mask:0xf bound_ctrl:1
	v_add_f32_dpp v174, v174, v174 quad_perm:[1,0,3,2] row_mask:0xf bank_mask:0xf bound_ctrl:1
	v_pk_fma_f32 v[222:223], v[76:77], v[188:189], v[222:223]
	v_pk_fma_f32 v[230:231], v[84:85], v[188:189], v[230:231]
	v_pk_fma_f32 v[224:225], v[78:79], v[190:191], v[224:225]
	v_pk_fma_f32 v[234:235], v[86:87], v[190:191], v[234:235]
	v_add_f32_dpp v172, v172, v172 quad_perm:[2,3,0,1] row_mask:0xf bank_mask:0xf bound_ctrl:1
	v_add_f32_dpp v174, v174, v174 quad_perm:[2,3,0,1] row_mask:0xf bank_mask:0xf bound_ctrl:1
	s_nop 0
	v_add_f32_dpp v172, v172, v172 row_half_mirror row_mask:0xf bank_mask:0xf bound_ctrl:1
	v_add_f32_dpp v174, v174, v174 row_half_mirror row_mask:0xf bank_mask:0xf bound_ctrl:1
	v_pk_fma_f32 v[72:73], v[192:193], v[172:173], v[218:219] op_sel_hi:[1,0,1]
	v_pk_fma_f32 v[80:81], v[192:193], v[174:175], v[226:227] op_sel_hi:[1,0,1]
	v_pk_fma_f32 v[74:75], v[194:195], v[172:173], v[220:221] op_sel_hi:[1,0,1]
	v_pk_fma_f32 v[82:83], v[194:195], v[174:175], v[228:229] op_sel_hi:[1,0,1]
	v_pk_fma_f32 v[76:77], v[196:197], v[172:173], v[222:223] op_sel_hi:[1,0,1]
	v_pk_fma_f32 v[84:85], v[196:197], v[174:175], v[230:231] op_sel_hi:[1,0,1]
	v_pk_fma_f32 v[78:79], v[198:199], v[172:173], v[224:225] op_sel_hi:[1,0,1]
	v_pk_fma_f32 v[86:87], v[198:199], v[174:175], v[234:235] op_sel_hi:[1,0,1]
	s_waitcnt lgkmcnt(0)
	v_pk_mul_f32 v[164:165], v[72:73], v[4:5]
	v_pk_mul_f32 v[166:167], v[80:81], v[4:5]
	ds_read_b128 v[48:51], v2 offset:16640
	v_pk_mul_f32 v[168:169], v[72:73], v[208:209]
	v_pk_mul_f32 v[170:171], v[80:81], v[208:209]
	ds_read_b128 v[52:55], v2 offset:16656
	v_pk_fma_f32 v[164:165], v[74:75], v[6:7], v[164:165]
	v_pk_fma_f32 v[166:167], v[82:83], v[6:7], v[166:167]
	ds_read_b128 v[176:179], v2 offset:4608
	v_pk_fma_f32 v[168:169], v[74:75], v[210:211], v[168:169]
	v_pk_fma_f32 v[170:171], v[82:83], v[210:211], v[170:171]
	ds_read_b128 v[180:183], v2 offset:4624
	v_pk_fma_f32 v[164:165], v[76:77], v[8:9], v[164:165]
	v_pk_fma_f32 v[166:167], v[84:85], v[8:9], v[166:167]
	ds_read_b128 v[200:203], v2 offset:12800
	v_pk_fma_f32 v[168:169], v[76:77], v[212:213], v[168:169]
	v_pk_fma_f32 v[170:171], v[84:85], v[212:213], v[170:171]
	ds_read_b128 v[204:207], v2 offset:12816
	v_pk_fma_f32 v[164:165], v[78:79], v[10:11], v[164:165]
	v_pk_fma_f32 v[166:167], v[86:87], v[10:11], v[166:167]
	ds_read_b64 v[216:217], v3 offset:41472
	v_pk_fma_f32 v[168:169], v[78:79], v[214:215], v[168:169]
	v_pk_fma_f32 v[170:171], v[86:87], v[214:215], v[170:171]
	ds_read_b128 v[184:187], v2 offset:512
	v_pk_mul_f32 v[218:219], v[26:27], v[40:41] op_sel_hi:[0,1]
	v_pk_mul_f32 v[226:227], v[26:27], v[40:41] op_sel:[1,0]
	ds_read_b128 v[188:191], v2 offset:528
	v_pk_mul_f32 v[220:221], v[26:27], v[42:43] op_sel_hi:[0,1]
	v_pk_mul_f32 v[228:229], v[26:27], v[42:43] op_sel:[1,0]
	ds_read_b128 v[192:195], v2 offset:8704
	v_pk_mul_f32 v[222:223], v[26:27], v[44:45] op_sel_hi:[0,1]
	v_pk_mul_f32 v[230:231], v[26:27], v[44:45] op_sel:[1,0]
	ds_read_b128 v[196:199], v2 offset:8720
	v_pk_mul_f32 v[224:225], v[26:27], v[46:47] op_sel_hi:[0,1]
	v_pk_mul_f32 v[234:235], v[26:27], v[46:47] op_sel:[1,0]
	v_add_f32_e32 v172, v164, v165
	v_add_f32_e32 v174, v166, v167
	v_add_f32_e32 v160, v168, v169
	v_add_f32_e32 v161, v170, v171
	v_pk_fma_f32 v[218:219], v[72:73], v[12:13], v[218:219]
	v_pk_fma_f32 v[226:227], v[80:81], v[12:13], v[226:227]
	v_pk_fma_f32 v[220:221], v[74:75], v[14:15], v[220:221]
	v_pk_fma_f32 v[228:229], v[82:83], v[14:15], v[228:229]
	v_add_f32_dpp v172, v172, v172 quad_perm:[1,0,3,2] row_mask:0xf bank_mask:0xf bound_ctrl:1
	v_add_f32_dpp v174, v174, v174 quad_perm:[1,0,3,2] row_mask:0xf bank_mask:0xf bound_ctrl:1
	v_add_f32_dpp v160, v160, v160 quad_perm:[1,0,3,2] row_mask:0xf bank_mask:0xf bound_ctrl:1
	v_add_f32_dpp v161, v161, v161 quad_perm:[1,0,3,2] row_mask:0xf bank_mask:0xf bound_ctrl:1
	v_pk_fma_f32 v[222:223], v[76:77], v[28:29], v[222:223]
	v_pk_fma_f32 v[230:231], v[84:85], v[28:29], v[230:231]
	v_pk_fma_f32 v[224:225], v[78:79], v[30:31], v[224:225]
	v_pk_fma_f32 v[234:235], v[86:87], v[30:31], v[234:235]
	v_add_f32_dpp v172, v172, v172 quad_perm:[2,3,0,1] row_mask:0xf bank_mask:0xf bound_ctrl:1
	v_add_f32_dpp v174, v174, v174 quad_perm:[2,3,0,1] row_mask:0xf bank_mask:0xf bound_ctrl:1
	v_add_f32_dpp v160, v160, v160 quad_perm:[2,3,0,1] row_mask:0xf bank_mask:0xf bound_ctrl:1
	v_add_f32_dpp v161, v161, v161 quad_perm:[2,3,0,1] row_mask:0xf bank_mask:0xf bound_ctrl:1
	v_add_f32_dpp v172, v172, v172 row_half_mirror row_mask:0xf bank_mask:0xf bound_ctrl:1
	v_add_f32_dpp v174, v174, v174 row_half_mirror row_mask:0xf bank_mask:0xf bound_ctrl:1
	v_add_f32_dpp v160, v160, v160 row_half_mirror row_mask:0xf bank_mask:0xf bound_ctrl:1
	v_add_f32_dpp v161, v161, v161 row_half_mirror row_mask:0xf bank_mask:0xf bound_ctrl:1
	v_pk_fma_f32 v[72:73], v[32:33], v[172:173], v[218:219] op_sel_hi:[1,0,1]
	v_pk_fma_f32 v[80:81], v[32:33], v[174:175], v[226:227] op_sel_hi:[1,0,1]
	v_pk_fma_f32 v[74:75], v[34:35], v[172:173], v[220:221] op_sel_hi:[1,0,1]
	v_pk_fma_f32 v[82:83], v[34:35], v[174:175], v[228:229] op_sel_hi:[1,0,1]
	v_pk_fma_f32 v[76:77], v[36:37], v[172:173], v[222:223] op_sel_hi:[1,0,1]
	v_pk_fma_f32 v[84:85], v[36:37], v[174:175], v[230:231] op_sel_hi:[1,0,1]
	v_pk_fma_f32 v[78:79], v[38:39], v[172:173], v[224:225] op_sel_hi:[1,0,1]
	v_pk_fma_f32 v[86:87], v[38:39], v[174:175], v[234:235] op_sel_hi:[1,0,1]
	s_waitcnt lgkmcnt(0)
	v_pk_mul_f32 v[164:165], v[72:73], v[176:177]
	v_pk_mul_f32 v[166:167], v[80:81], v[176:177]
	ds_read_b128 v[208:211], v2 offset:16896
	v_pk_mul_f32 v[168:169], v[72:73], v[48:49]
	v_pk_mul_f32 v[170:171], v[80:81], v[48:49]
	ds_read_b128 v[212:215], v2 offset:16912
	v_pk_fma_f32 v[164:165], v[74:75], v[178:179], v[164:165]
	v_pk_fma_f32 v[166:167], v[82:83], v[178:179], v[166:167]
	ds_read_b128 v[4:7], v2 offset:4864
	v_pk_fma_f32 v[168:169], v[74:75], v[50:51], v[168:169]
	v_pk_fma_f32 v[170:171], v[82:83], v[50:51], v[170:171]
	ds_read_b128 v[8:11], v2 offset:4880
	v_pk_fma_f32 v[164:165], v[76:77], v[180:181], v[164:165]
	v_pk_fma_f32 v[166:167], v[84:85], v[180:181], v[166:167]
	ds_read_b128 v[40:43], v2 offset:13056
	v_pk_fma_f32 v[168:169], v[76:77], v[52:53], v[168:169]
	v_pk_fma_f32 v[170:171], v[84:85], v[52:53], v[170:171]
	ds_read_b128 v[44:47], v2 offset:13072
	v_pk_fma_f32 v[164:165], v[78:79], v[182:183], v[164:165]
	v_pk_fma_f32 v[166:167], v[86:87], v[182:183], v[166:167]
	ds_read_b64 v[26:27], v3 offset:41728
	v_pk_fma_f32 v[168:169], v[78:79], v[54:55], v[168:169]
	v_pk_fma_f32 v[170:171], v[86:87], v[54:55], v[170:171]
	ds_read_b128 v[12:15], v2 offset:768
	v_pk_mul_f32 v[218:219], v[216:217], v[200:201] op_sel_hi:[0,1]
	v_pk_mul_f32 v[226:227], v[216:217], v[200:201] op_sel:[1,0]
	ds_read_b128 v[28:31], v2 offset:784
	v_pk_mul_f32 v[220:221], v[216:217], v[202:203] op_sel_hi:[0,1]
	v_pk_mul_f32 v[228:229], v[216:217], v[202:203] op_sel:[1,0]
	ds_read_b128 v[32:35], v2 offset:8960
	v_pk_mul_f32 v[222:223], v[216:217], v[204:205] op_sel_hi:[0,1]
	v_pk_mul_f32 v[230:231], v[216:217], v[204:205] op_sel:[1,0]
	ds_read_b128 v[36:39], v2 offset:8976
	v_pk_mul_f32 v[224:225], v[216:217], v[206:207] op_sel_hi:[0,1]
	v_pk_mul_f32 v[234:235], v[216:217], v[206:207] op_sel:[1,0]
	v_add_f32_e32 v172, v164, v165
	v_add_f32_e32 v174, v166, v167
	v_add_f32_e32 v244, v168, v169
	v_add_f32_e32 v245, v170, v171
	v_pk_fma_f32 v[218:219], v[72:73], v[184:185], v[218:219]
	v_pk_fma_f32 v[226:227], v[80:81], v[184:185], v[226:227]
	v_pk_fma_f32 v[220:221], v[74:75], v[186:187], v[220:221]
	v_pk_fma_f32 v[228:229], v[82:83], v[186:187], v[228:229]
	v_add_f32_dpp v172, v172, v172 quad_perm:[1,0,3,2] row_mask:0xf bank_mask:0xf bound_ctrl:1
	v_add_f32_dpp v174, v174, v174 quad_perm:[1,0,3,2] row_mask:0xf bank_mask:0xf bound_ctrl:1
	v_add_f32_dpp v244, v244, v244 quad_perm:[1,0,3,2] row_mask:0xf bank_mask:0xf bound_ctrl:1
	v_add_f32_dpp v245, v245, v245 quad_perm:[1,0,3,2] row_mask:0xf bank_mask:0xf bound_ctrl:1
	v_pk_fma_f32 v[222:223], v[76:77], v[188:189], v[222:223]
	v_pk_fma_f32 v[230:231], v[84:85], v[188:189], v[230:231]
	v_pk_fma_f32 v[224:225], v[78:79], v[190:191], v[224:225]
	v_pk_fma_f32 v[234:235], v[86:87], v[190:191], v[234:235]
	v_add_f32_dpp v172, v172, v172 quad_perm:[2,3,0,1] row_mask:0xf bank_mask:0xf bound_ctrl:1
	v_add_f32_dpp v174, v174, v174 quad_perm:[2,3,0,1] row_mask:0xf bank_mask:0xf bound_ctrl:1
	v_add_f32_dpp v244, v244, v244 quad_perm:[2,3,0,1] row_mask:0xf bank_mask:0xf bound_ctrl:1
	v_add_f32_dpp v245, v245, v245 quad_perm:[2,3,0,1] row_mask:0xf bank_mask:0xf bound_ctrl:1
	v_add_f32_dpp v172, v172, v172 row_half_mirror row_mask:0xf bank_mask:0xf bound_ctrl:1
	v_add_f32_dpp v174, v174, v174 row_half_mirror row_mask:0xf bank_mask:0xf bound_ctrl:1
	v_add_f32_dpp v244, v244, v244 row_half_mirror row_mask:0xf bank_mask:0xf bound_ctrl:1
	v_add_f32_dpp v245, v245, v245 row_half_mirror row_mask:0xf bank_mask:0xf bound_ctrl:1
	v_pk_fma_f32 v[72:73], v[192:193], v[172:173], v[218:219] op_sel_hi:[1,0,1]
	v_pk_fma_f32 v[80:81], v[192:193], v[174:175], v[226:227] op_sel_hi:[1,0,1]
	v_pk_fma_f32 v[74:75], v[194:195], v[172:173], v[220:221] op_sel_hi:[1,0,1]
	v_pk_fma_f32 v[82:83], v[194:195], v[174:175], v[228:229] op_sel_hi:[1,0,1]
	v_pk_fma_f32 v[76:77], v[196:197], v[172:173], v[222:223] op_sel_hi:[1,0,1]
	v_pk_fma_f32 v[84:85], v[196:197], v[174:175], v[230:231] op_sel_hi:[1,0,1]
	v_pk_fma_f32 v[78:79], v[198:199], v[172:173], v[224:225] op_sel_hi:[1,0,1]
	v_pk_fma_f32 v[86:87], v[198:199], v[174:175], v[234:235] op_sel_hi:[1,0,1]
	ds_write2_b64 v246, v[160:161], v[244:245] offset1:32
	s_waitcnt lgkmcnt(1)
	v_pk_mul_f32 v[164:165], v[72:73], v[4:5]
	v_pk_mul_f32 v[166:167], v[80:81], v[4:5]
	ds_read_b128 v[48:51], v2 offset:17152
	v_pk_mul_f32 v[168:169], v[72:73], v[208:209]
	v_pk_mul_f32 v[170:171], v[80:81], v[208:209]
	ds_read_b128 v[52:55], v2 offset:17168
	v_pk_fma_f32 v[164:165], v[74:75], v[6:7], v[164:165]
	v_pk_fma_f32 v[166:167], v[82:83], v[6:7], v[166:167]
	ds_read_b128 v[176:179], v2 offset:5120
	v_pk_fma_f32 v[168:169], v[74:75], v[210:211], v[168:169]
	v_pk_fma_f32 v[170:171], v[82:83], v[210:211], v[170:171]
	ds_read_b128 v[180:183], v2 offset:5136
	v_pk_fma_f32 v[164:165], v[76:77], v[8:9], v[164:165]
	v_pk_fma_f32 v[166:167], v[84:85], v[8:9], v[166:167]
	ds_read_b128 v[200:203], v2 offset:13312
	v_pk_fma_f32 v[168:169], v[76:77], v[212:213], v[168:169]
	v_pk_fma_f32 v[170:171], v[84:85], v[212:213], v[170:171]
	ds_read_b128 v[204:207], v2 offset:13328
	v_pk_fma_f32 v[164:165], v[78:79], v[10:11], v[164:165]
	v_pk_fma_f32 v[166:167], v[86:87], v[10:11], v[166:167]
	ds_read_b64 v[216:217], v3 offset:41984
	v_pk_fma_f32 v[168:169], v[78:79], v[214:215], v[168:169]
	v_pk_fma_f32 v[170:171], v[86:87], v[214:215], v[170:171]
	ds_read_b128 v[184:187], v2 offset:1024
	v_pk_mul_f32 v[218:219], v[26:27], v[40:41] op_sel_hi:[0,1]
	v_pk_mul_f32 v[226:227], v[26:27], v[40:41] op_sel:[1,0]
	ds_read_b128 v[188:191], v2 offset:1040
	v_pk_mul_f32 v[220:221], v[26:27], v[42:43] op_sel_hi:[0,1]
	v_pk_mul_f32 v[228:229], v[26:27], v[42:43] op_sel:[1,0]
	ds_read_b128 v[192:195], v2 offset:9216
	v_pk_mul_f32 v[222:223], v[26:27], v[44:45] op_sel_hi:[0,1]
	v_pk_mul_f32 v[230:231], v[26:27], v[44:45] op_sel:[1,0]
	ds_read_b128 v[196:199], v2 offset:9232
	v_pk_mul_f32 v[224:225], v[26:27], v[46:47] op_sel_hi:[0,1]
	v_pk_mul_f32 v[234:235], v[26:27], v[46:47] op_sel:[1,0]
	v_add_f32_e32 v172, v164, v165
	v_add_f32_e32 v174, v166, v167
	v_add_f32_e32 v160, v168, v169
	v_add_f32_e32 v161, v170, v171
	v_pk_fma_f32 v[218:219], v[72:73], v[12:13], v[218:219]
	v_pk_fma_f32 v[226:227], v[80:81], v[12:13], v[226:227]
	v_pk_fma_f32 v[220:221], v[74:75], v[14:15], v[220:221]
	v_pk_fma_f32 v[228:229], v[82:83], v[14:15], v[228:229]
	v_add_f32_dpp v172, v172, v172 quad_perm:[1,0,3,2] row_mask:0xf bank_mask:0xf bound_ctrl:1
	v_add_f32_dpp v174, v174, v174 quad_perm:[1,0,3,2] row_mask:0xf bank_mask:0xf bound_ctrl:1
	v_add_f32_dpp v160, v160, v160 quad_perm:[1,0,3,2] row_mask:0xf bank_mask:0xf bound_ctrl:1
	v_add_f32_dpp v161, v161, v161 quad_perm:[1,0,3,2] row_mask:0xf bank_mask:0xf bound_ctrl:1
	v_pk_fma_f32 v[222:223], v[76:77], v[28:29], v[222:223]
	v_pk_fma_f32 v[230:231], v[84:85], v[28:29], v[230:231]
	v_pk_fma_f32 v[224:225], v[78:79], v[30:31], v[224:225]
	v_pk_fma_f32 v[234:235], v[86:87], v[30:31], v[234:235]
	v_add_f32_dpp v172, v172, v172 quad_perm:[2,3,0,1] row_mask:0xf bank_mask:0xf bound_ctrl:1
	v_add_f32_dpp v174, v174, v174 quad_perm:[2,3,0,1] row_mask:0xf bank_mask:0xf bound_ctrl:1
	v_add_f32_dpp v160, v160, v160 quad_perm:[2,3,0,1] row_mask:0xf bank_mask:0xf bound_ctrl:1
	v_add_f32_dpp v161, v161, v161 quad_perm:[2,3,0,1] row_mask:0xf bank_mask:0xf bound_ctrl:1
	v_add_f32_dpp v172, v172, v172 row_half_mirror row_mask:0xf bank_mask:0xf bound_ctrl:1
	v_add_f32_dpp v174, v174, v174 row_half_mirror row_mask:0xf bank_mask:0xf bound_ctrl:1
	v_add_f32_dpp v160, v160, v160 row_half_mirror row_mask:0xf bank_mask:0xf bound_ctrl:1
	v_add_f32_dpp v161, v161, v161 row_half_mirror row_mask:0xf bank_mask:0xf bound_ctrl:1
	v_pk_fma_f32 v[72:73], v[32:33], v[172:173], v[218:219] op_sel_hi:[1,0,1]
	v_pk_fma_f32 v[80:81], v[32:33], v[174:175], v[226:227] op_sel_hi:[1,0,1]
	v_pk_fma_f32 v[74:75], v[34:35], v[172:173], v[220:221] op_sel_hi:[1,0,1]
	v_pk_fma_f32 v[82:83], v[34:35], v[174:175], v[228:229] op_sel_hi:[1,0,1]
	v_pk_fma_f32 v[76:77], v[36:37], v[172:173], v[222:223] op_sel_hi:[1,0,1]
	v_pk_fma_f32 v[84:85], v[36:37], v[174:175], v[230:231] op_sel_hi:[1,0,1]
	v_pk_fma_f32 v[78:79], v[38:39], v[172:173], v[224:225] op_sel_hi:[1,0,1]
	v_pk_fma_f32 v[86:87], v[38:39], v[174:175], v[234:235] op_sel_hi:[1,0,1]
	s_waitcnt lgkmcnt(0)
	v_pk_mul_f32 v[164:165], v[72:73], v[176:177]
	v_pk_mul_f32 v[166:167], v[80:81], v[176:177]
	ds_read_b128 v[208:211], v2 offset:17408
	v_pk_mul_f32 v[168:169], v[72:73], v[48:49]
	v_pk_mul_f32 v[170:171], v[80:81], v[48:49]
	ds_read_b128 v[212:215], v2 offset:17424
	v_pk_fma_f32 v[164:165], v[74:75], v[178:179], v[164:165]
	v_pk_fma_f32 v[166:167], v[82:83], v[178:179], v[166:167]
	ds_read_b128 v[4:7], v2 offset:5376
	v_pk_fma_f32 v[168:169], v[74:75], v[50:51], v[168:169]
	v_pk_fma_f32 v[170:171], v[82:83], v[50:51], v[170:171]
	ds_read_b128 v[8:11], v2 offset:5392
	v_pk_fma_f32 v[164:165], v[76:77], v[180:181], v[164:165]
	v_pk_fma_f32 v[166:167], v[84:85], v[180:181], v[166:167]
	ds_read_b128 v[40:43], v2 offset:13568
	v_pk_fma_f32 v[168:169], v[76:77], v[52:53], v[168:169]
	v_pk_fma_f32 v[170:171], v[84:85], v[52:53], v[170:171]
	ds_read_b128 v[44:47], v2 offset:13584
	v_pk_fma_f32 v[164:165], v[78:79], v[182:183], v[164:165]
	v_pk_fma_f32 v[166:167], v[86:87], v[182:183], v[166:167]
	ds_read_b64 v[26:27], v3 offset:42240
	v_pk_fma_f32 v[168:169], v[78:79], v[54:55], v[168:169]
	v_pk_fma_f32 v[170:171], v[86:87], v[54:55], v[170:171]
	ds_read_b128 v[12:15], v2 offset:1280
	v_pk_mul_f32 v[218:219], v[216:217], v[200:201] op_sel_hi:[0,1]
	v_pk_mul_f32 v[226:227], v[216:217], v[200:201] op_sel:[1,0]
	ds_read_b128 v[28:31], v2 offset:1296
	v_pk_mul_f32 v[220:221], v[216:217], v[202:203] op_sel_hi:[0,1]
	v_pk_mul_f32 v[228:229], v[216:217], v[202:203] op_sel:[1,0]
	ds_read_b128 v[32:35], v2 offset:9472
	v_pk_mul_f32 v[222:223], v[216:217], v[204:205] op_sel_hi:[0,1]
	v_pk_mul_f32 v[230:231], v[216:217], v[204:205] op_sel:[1,0]
	ds_read_b128 v[36:39], v2 offset:9488
	v_pk_mul_f32 v[224:225], v[216:217], v[206:207] op_sel_hi:[0,1]
	v_pk_mul_f32 v[234:235], v[216:217], v[206:207] op_sel:[1,0]
	v_add_f32_e32 v172, v164, v165
	v_add_f32_e32 v174, v166, v167
	v_add_f32_e32 v244, v168, v169
	v_add_f32_e32 v245, v170, v171
	v_pk_fma_f32 v[218:219], v[72:73], v[184:185], v[218:219]
	v_pk_fma_f32 v[226:227], v[80:81], v[184:185], v[226:227]
	v_pk_fma_f32 v[220:221], v[74:75], v[186:187], v[220:221]
	v_pk_fma_f32 v[228:229], v[82:83], v[186:187], v[228:229]
	v_add_f32_dpp v172, v172, v172 quad_perm:[1,0,3,2] row_mask:0xf bank_mask:0xf bound_ctrl:1
	v_add_f32_dpp v174, v174, v174 quad_perm:[1,0,3,2] row_mask:0xf bank_mask:0xf bound_ctrl:1
	v_add_f32_dpp v244, v244, v244 quad_perm:[1,0,3,2] row_mask:0xf bank_mask:0xf bound_ctrl:1
	v_add_f32_dpp v245, v245, v245 quad_perm:[1,0,3,2] row_mask:0xf bank_mask:0xf bound_ctrl:1
	v_pk_fma_f32 v[222:223], v[76:77], v[188:189], v[222:223]
	v_pk_fma_f32 v[230:231], v[84:85], v[188:189], v[230:231]
	v_pk_fma_f32 v[224:225], v[78:79], v[190:191], v[224:225]
	v_pk_fma_f32 v[234:235], v[86:87], v[190:191], v[234:235]
	v_add_f32_dpp v172, v172, v172 quad_perm:[2,3,0,1] row_mask:0xf bank_mask:0xf bound_ctrl:1
	v_add_f32_dpp v174, v174, v174 quad_perm:[2,3,0,1] row_mask:0xf bank_mask:0xf bound_ctrl:1
	v_add_f32_dpp v244, v244, v244 quad_perm:[2,3,0,1] row_mask:0xf bank_mask:0xf bound_ctrl:1
	v_add_f32_dpp v245, v245, v245 quad_perm:[2,3,0,1] row_mask:0xf bank_mask:0xf bound_ctrl:1
	v_add_f32_dpp v172, v172, v172 row_half_mirror row_mask:0xf bank_mask:0xf bound_ctrl:1
	v_add_f32_dpp v174, v174, v174 row_half_mirror row_mask:0xf bank_mask:0xf bound_ctrl:1
	v_add_f32_dpp v244, v244, v244 row_half_mirror row_mask:0xf bank_mask:0xf bound_ctrl:1
	v_add_f32_dpp v245, v245, v245 row_half_mirror row_mask:0xf bank_mask:0xf bound_ctrl:1
	v_pk_fma_f32 v[72:73], v[192:193], v[172:173], v[218:219] op_sel_hi:[1,0,1]
	v_pk_fma_f32 v[80:81], v[192:193], v[174:175], v[226:227] op_sel_hi:[1,0,1]
	v_pk_fma_f32 v[74:75], v[194:195], v[172:173], v[220:221] op_sel_hi:[1,0,1]
	v_pk_fma_f32 v[82:83], v[194:195], v[174:175], v[228:229] op_sel_hi:[1,0,1]
	v_pk_fma_f32 v[76:77], v[196:197], v[172:173], v[222:223] op_sel_hi:[1,0,1]
	v_pk_fma_f32 v[84:85], v[196:197], v[174:175], v[230:231] op_sel_hi:[1,0,1]
	v_pk_fma_f32 v[78:79], v[198:199], v[172:173], v[224:225] op_sel_hi:[1,0,1]
	v_pk_fma_f32 v[86:87], v[198:199], v[174:175], v[234:235] op_sel_hi:[1,0,1]
	ds_write2_b64 v246, v[160:161], v[244:245] offset0:64 offset1:96
	s_waitcnt lgkmcnt(1)
	v_pk_mul_f32 v[164:165], v[72:73], v[4:5]
	v_pk_mul_f32 v[166:167], v[80:81], v[4:5]
	ds_read_b128 v[48:51], v2 offset:17664
	v_pk_mul_f32 v[168:169], v[72:73], v[208:209]
	v_pk_mul_f32 v[170:171], v[80:81], v[208:209]
	ds_read_b128 v[52:55], v2 offset:17680
	v_pk_fma_f32 v[164:165], v[74:75], v[6:7], v[164:165]
	v_pk_fma_f32 v[166:167], v[82:83], v[6:7], v[166:167]
	ds_read_b128 v[176:179], v2 offset:5632
	v_pk_fma_f32 v[168:169], v[74:75], v[210:211], v[168:169]
	v_pk_fma_f32 v[170:171], v[82:83], v[210:211], v[170:171]
	ds_read_b128 v[180:183], v2 offset:5648
	v_pk_fma_f32 v[164:165], v[76:77], v[8:9], v[164:165]
	v_pk_fma_f32 v[166:167], v[84:85], v[8:9], v[166:167]
	ds_read_b128 v[200:203], v2 offset:13824
	v_pk_fma_f32 v[168:169], v[76:77], v[212:213], v[168:169]
	v_pk_fma_f32 v[170:171], v[84:85], v[212:213], v[170:171]
	ds_read_b128 v[204:207], v2 offset:13840
	v_pk_fma_f32 v[164:165], v[78:79], v[10:11], v[164:165]
	v_pk_fma_f32 v[166:167], v[86:87], v[10:11], v[166:167]
	ds_read_b64 v[216:217], v3 offset:42496
	v_pk_fma_f32 v[168:169], v[78:79], v[214:215], v[168:169]
	v_pk_fma_f32 v[170:171], v[86:87], v[214:215], v[170:171]
	ds_read_b128 v[184:187], v2 offset:1536
	v_pk_mul_f32 v[218:219], v[26:27], v[40:41] op_sel_hi:[0,1]
	v_pk_mul_f32 v[226:227], v[26:27], v[40:41] op_sel:[1,0]
	ds_read_b128 v[188:191], v2 offset:1552
	v_pk_mul_f32 v[220:221], v[26:27], v[42:43] op_sel_hi:[0,1]
	v_pk_mul_f32 v[228:229], v[26:27], v[42:43] op_sel:[1,0]
	ds_read_b128 v[192:195], v2 offset:9728
	v_pk_mul_f32 v[222:223], v[26:27], v[44:45] op_sel_hi:[0,1]
	v_pk_mul_f32 v[230:231], v[26:27], v[44:45] op_sel:[1,0]
	ds_read_b128 v[196:199], v2 offset:9744
	v_pk_mul_f32 v[224:225], v[26:27], v[46:47] op_sel_hi:[0,1]
	v_pk_mul_f32 v[234:235], v[26:27], v[46:47] op_sel:[1,0]
	v_add_f32_e32 v172, v164, v165
	v_add_f32_e32 v174, v166, v167
	v_add_f32_e32 v160, v168, v169
	v_add_f32_e32 v161, v170, v171
	v_pk_fma_f32 v[218:219], v[72:73], v[12:13], v[218:219]
	v_pk_fma_f32 v[226:227], v[80:81], v[12:13], v[226:227]
	v_pk_fma_f32 v[220:221], v[74:75], v[14:15], v[220:221]
	v_pk_fma_f32 v[228:229], v[82:83], v[14:15], v[228:229]
	v_add_f32_dpp v172, v172, v172 quad_perm:[1,0,3,2] row_mask:0xf bank_mask:0xf bound_ctrl:1
	v_add_f32_dpp v174, v174, v174 quad_perm:[1,0,3,2] row_mask:0xf bank_mask:0xf bound_ctrl:1
	v_add_f32_dpp v160, v160, v160 quad_perm:[1,0,3,2] row_mask:0xf bank_mask:0xf bound_ctrl:1
	v_add_f32_dpp v161, v161, v161 quad_perm:[1,0,3,2] row_mask:0xf bank_mask:0xf bound_ctrl:1
	v_pk_fma_f32 v[222:223], v[76:77], v[28:29], v[222:223]
	v_pk_fma_f32 v[230:231], v[84:85], v[28:29], v[230:231]
	v_pk_fma_f32 v[224:225], v[78:79], v[30:31], v[224:225]
	v_pk_fma_f32 v[234:235], v[86:87], v[30:31], v[234:235]
	v_add_f32_dpp v172, v172, v172 quad_perm:[2,3,0,1] row_mask:0xf bank_mask:0xf bound_ctrl:1
	v_add_f32_dpp v174, v174, v174 quad_perm:[2,3,0,1] row_mask:0xf bank_mask:0xf bound_ctrl:1
	v_add_f32_dpp v160, v160, v160 quad_perm:[2,3,0,1] row_mask:0xf bank_mask:0xf bound_ctrl:1
	v_add_f32_dpp v161, v161, v161 quad_perm:[2,3,0,1] row_mask:0xf bank_mask:0xf bound_ctrl:1
	v_add_f32_dpp v172, v172, v172 row_half_mirror row_mask:0xf bank_mask:0xf bound_ctrl:1
	v_add_f32_dpp v174, v174, v174 row_half_mirror row_mask:0xf bank_mask:0xf bound_ctrl:1
	v_add_f32_dpp v160, v160, v160 row_half_mirror row_mask:0xf bank_mask:0xf bound_ctrl:1
	v_add_f32_dpp v161, v161, v161 row_half_mirror row_mask:0xf bank_mask:0xf bound_ctrl:1
	v_pk_fma_f32 v[72:73], v[32:33], v[172:173], v[218:219] op_sel_hi:[1,0,1]
	v_pk_fma_f32 v[80:81], v[32:33], v[174:175], v[226:227] op_sel_hi:[1,0,1]
	v_pk_fma_f32 v[74:75], v[34:35], v[172:173], v[220:221] op_sel_hi:[1,0,1]
	v_pk_fma_f32 v[82:83], v[34:35], v[174:175], v[228:229] op_sel_hi:[1,0,1]
	v_pk_fma_f32 v[76:77], v[36:37], v[172:173], v[222:223] op_sel_hi:[1,0,1]
	v_pk_fma_f32 v[84:85], v[36:37], v[174:175], v[230:231] op_sel_hi:[1,0,1]
	v_pk_fma_f32 v[78:79], v[38:39], v[172:173], v[224:225] op_sel_hi:[1,0,1]
	v_pk_fma_f32 v[86:87], v[38:39], v[174:175], v[234:235] op_sel_hi:[1,0,1]
	s_waitcnt lgkmcnt(0)
	v_pk_mul_f32 v[164:165], v[72:73], v[176:177]
	v_pk_mul_f32 v[166:167], v[80:81], v[176:177]
	ds_read_b128 v[208:211], v2 offset:17920
	v_pk_mul_f32 v[168:169], v[72:73], v[48:49]
	v_pk_mul_f32 v[170:171], v[80:81], v[48:49]
	ds_read_b128 v[212:215], v2 offset:17936
	v_pk_fma_f32 v[164:165], v[74:75], v[178:179], v[164:165]
	v_pk_fma_f32 v[166:167], v[82:83], v[178:179], v[166:167]
	ds_read_b128 v[4:7], v2 offset:5888
	v_pk_fma_f32 v[168:169], v[74:75], v[50:51], v[168:169]
	v_pk_fma_f32 v[170:171], v[82:83], v[50:51], v[170:171]
	ds_read_b128 v[8:11], v2 offset:5904
	v_pk_fma_f32 v[164:165], v[76:77], v[180:181], v[164:165]
	v_pk_fma_f32 v[166:167], v[84:85], v[180:181], v[166:167]
	ds_read_b128 v[40:43], v2 offset:14080
	v_pk_fma_f32 v[168:169], v[76:77], v[52:53], v[168:169]
	v_pk_fma_f32 v[170:171], v[84:85], v[52:53], v[170:171]
	ds_read_b128 v[44:47], v2 offset:14096
	v_pk_fma_f32 v[164:165], v[78:79], v[182:183], v[164:165]
	v_pk_fma_f32 v[166:167], v[86:87], v[182:183], v[166:167]
	ds_read_b64 v[26:27], v3 offset:42752
	v_pk_fma_f32 v[168:169], v[78:79], v[54:55], v[168:169]
	v_pk_fma_f32 v[170:171], v[86:87], v[54:55], v[170:171]
	ds_read_b128 v[12:15], v2 offset:1792
	v_pk_mul_f32 v[218:219], v[216:217], v[200:201] op_sel_hi:[0,1]
	v_pk_mul_f32 v[226:227], v[216:217], v[200:201] op_sel:[1,0]
	ds_read_b128 v[28:31], v2 offset:1808
	v_pk_mul_f32 v[220:221], v[216:217], v[202:203] op_sel_hi:[0,1]
	v_pk_mul_f32 v[228:229], v[216:217], v[202:203] op_sel:[1,0]
	ds_read_b128 v[32:35], v2 offset:9984
	v_pk_mul_f32 v[222:223], v[216:217], v[204:205] op_sel_hi:[0,1]
	v_pk_mul_f32 v[230:231], v[216:217], v[204:205] op_sel:[1,0]
	ds_read_b128 v[36:39], v2 offset:10000
	v_pk_mul_f32 v[224:225], v[216:217], v[206:207] op_sel_hi:[0,1]
	v_pk_mul_f32 v[234:235], v[216:217], v[206:207] op_sel:[1,0]
	v_add_f32_e32 v172, v164, v165
	v_add_f32_e32 v174, v166, v167
	v_add_f32_e32 v244, v168, v169
	v_add_f32_e32 v245, v170, v171
	v_pk_fma_f32 v[218:219], v[72:73], v[184:185], v[218:219]
	v_pk_fma_f32 v[226:227], v[80:81], v[184:185], v[226:227]
	v_pk_fma_f32 v[220:221], v[74:75], v[186:187], v[220:221]
	v_pk_fma_f32 v[228:229], v[82:83], v[186:187], v[228:229]
	v_add_f32_dpp v172, v172, v172 quad_perm:[1,0,3,2] row_mask:0xf bank_mask:0xf bound_ctrl:1
	v_add_f32_dpp v174, v174, v174 quad_perm:[1,0,3,2] row_mask:0xf bank_mask:0xf bound_ctrl:1
	v_add_f32_dpp v244, v244, v244 quad_perm:[1,0,3,2] row_mask:0xf bank_mask:0xf bound_ctrl:1
	v_add_f32_dpp v245, v245, v245 quad_perm:[1,0,3,2] row_mask:0xf bank_mask:0xf bound_ctrl:1
	v_pk_fma_f32 v[222:223], v[76:77], v[188:189], v[222:223]
	v_pk_fma_f32 v[230:231], v[84:85], v[188:189], v[230:231]
	v_pk_fma_f32 v[224:225], v[78:79], v[190:191], v[224:225]
	v_pk_fma_f32 v[234:235], v[86:87], v[190:191], v[234:235]
	v_add_f32_dpp v172, v172, v172 quad_perm:[2,3,0,1] row_mask:0xf bank_mask:0xf bound_ctrl:1
	v_add_f32_dpp v174, v174, v174 quad_perm:[2,3,0,1] row_mask:0xf bank_mask:0xf bound_ctrl:1
	v_add_f32_dpp v244, v244, v244 quad_perm:[2,3,0,1] row_mask:0xf bank_mask:0xf bound_ctrl:1
	v_add_f32_dpp v245, v245, v245 quad_perm:[2,3,0,1] row_mask:0xf bank_mask:0xf bound_ctrl:1
	v_add_f32_dpp v172, v172, v172 row_half_mirror row_mask:0xf bank_mask:0xf bound_ctrl:1
	v_add_f32_dpp v174, v174, v174 row_half_mirror row_mask:0xf bank_mask:0xf bound_ctrl:1
	v_add_f32_dpp v244, v244, v244 row_half_mirror row_mask:0xf bank_mask:0xf bound_ctrl:1
	v_add_f32_dpp v245, v245, v245 row_half_mirror row_mask:0xf bank_mask:0xf bound_ctrl:1
	v_pk_fma_f32 v[72:73], v[192:193], v[172:173], v[218:219] op_sel_hi:[1,0,1]
	v_pk_fma_f32 v[80:81], v[192:193], v[174:175], v[226:227] op_sel_hi:[1,0,1]
	v_pk_fma_f32 v[74:75], v[194:195], v[172:173], v[220:221] op_sel_hi:[1,0,1]
	v_pk_fma_f32 v[82:83], v[194:195], v[174:175], v[228:229] op_sel_hi:[1,0,1]
	v_pk_fma_f32 v[76:77], v[196:197], v[172:173], v[222:223] op_sel_hi:[1,0,1]
	v_pk_fma_f32 v[84:85], v[196:197], v[174:175], v[230:231] op_sel_hi:[1,0,1]
	v_pk_fma_f32 v[78:79], v[198:199], v[172:173], v[224:225] op_sel_hi:[1,0,1]
	v_pk_fma_f32 v[86:87], v[198:199], v[174:175], v[234:235] op_sel_hi:[1,0,1]
	ds_write2_b64 v246, v[160:161], v[244:245] offset0:128 offset1:160
	s_waitcnt lgkmcnt(1)
	v_pk_mul_f32 v[164:165], v[72:73], v[4:5]
	v_pk_mul_f32 v[166:167], v[80:81], v[4:5]
	ds_read_b128 v[48:51], v2 offset:18176
	v_pk_mul_f32 v[168:169], v[72:73], v[208:209]
	v_pk_mul_f32 v[170:171], v[80:81], v[208:209]
	ds_read_b128 v[52:55], v2 offset:18192
	v_pk_fma_f32 v[164:165], v[74:75], v[6:7], v[164:165]
	v_pk_fma_f32 v[166:167], v[82:83], v[6:7], v[166:167]
	ds_read_b128 v[176:179], v2 offset:6144
	v_pk_fma_f32 v[168:169], v[74:75], v[210:211], v[168:169]
	v_pk_fma_f32 v[170:171], v[82:83], v[210:211], v[170:171]
	ds_read_b128 v[180:183], v2 offset:6160
	v_pk_fma_f32 v[164:165], v[76:77], v[8:9], v[164:165]
	v_pk_fma_f32 v[166:167], v[84:85], v[8:9], v[166:167]
	ds_read_b128 v[200:203], v2 offset:14336
	v_pk_fma_f32 v[168:169], v[76:77], v[212:213], v[168:169]
	v_pk_fma_f32 v[170:171], v[84:85], v[212:213], v[170:171]
	ds_read_b128 v[204:207], v2 offset:14352
	v_pk_fma_f32 v[164:165], v[78:79], v[10:11], v[164:165]
	v_pk_fma_f32 v[166:167], v[86:87], v[10:11], v[166:167]
	ds_read_b64 v[216:217], v3 offset:43008
	v_pk_fma_f32 v[168:169], v[78:79], v[214:215], v[168:169]
	v_pk_fma_f32 v[170:171], v[86:87], v[214:215], v[170:171]
	ds_read_b128 v[184:187], v2 offset:2048
	v_pk_mul_f32 v[218:219], v[26:27], v[40:41] op_sel_hi:[0,1]
	v_pk_mul_f32 v[226:227], v[26:27], v[40:41] op_sel:[1,0]
	ds_read_b128 v[188:191], v2 offset:2064
	v_pk_mul_f32 v[220:221], v[26:27], v[42:43] op_sel_hi:[0,1]
	v_pk_mul_f32 v[228:229], v[26:27], v[42:43] op_sel:[1,0]
	ds_read_b128 v[192:195], v2 offset:10240
	v_pk_mul_f32 v[222:223], v[26:27], v[44:45] op_sel_hi:[0,1]
	v_pk_mul_f32 v[230:231], v[26:27], v[44:45] op_sel:[1,0]
	ds_read_b128 v[196:199], v2 offset:10256
	v_pk_mul_f32 v[224:225], v[26:27], v[46:47] op_sel_hi:[0,1]
	v_pk_mul_f32 v[234:235], v[26:27], v[46:47] op_sel:[1,0]
	v_add_f32_e32 v172, v164, v165
	v_add_f32_e32 v174, v166, v167
	v_add_f32_e32 v160, v168, v169
	v_add_f32_e32 v161, v170, v171
	v_pk_fma_f32 v[218:219], v[72:73], v[12:13], v[218:219]
	v_pk_fma_f32 v[226:227], v[80:81], v[12:13], v[226:227]
	v_pk_fma_f32 v[220:221], v[74:75], v[14:15], v[220:221]
	v_pk_fma_f32 v[228:229], v[82:83], v[14:15], v[228:229]
	v_add_f32_dpp v172, v172, v172 quad_perm:[1,0,3,2] row_mask:0xf bank_mask:0xf bound_ctrl:1
	v_add_f32_dpp v174, v174, v174 quad_perm:[1,0,3,2] row_mask:0xf bank_mask:0xf bound_ctrl:1
	v_add_f32_dpp v160, v160, v160 quad_perm:[1,0,3,2] row_mask:0xf bank_mask:0xf bound_ctrl:1
	v_add_f32_dpp v161, v161, v161 quad_perm:[1,0,3,2] row_mask:0xf bank_mask:0xf bound_ctrl:1
	v_pk_fma_f32 v[222:223], v[76:77], v[28:29], v[222:223]
	v_pk_fma_f32 v[230:231], v[84:85], v[28:29], v[230:231]
	v_pk_fma_f32 v[224:225], v[78:79], v[30:31], v[224:225]
	v_pk_fma_f32 v[234:235], v[86:87], v[30:31], v[234:235]
	v_add_f32_dpp v172, v172, v172 quad_perm:[2,3,0,1] row_mask:0xf bank_mask:0xf bound_ctrl:1
	v_add_f32_dpp v174, v174, v174 quad_perm:[2,3,0,1] row_mask:0xf bank_mask:0xf bound_ctrl:1
	v_add_f32_dpp v160, v160, v160 quad_perm:[2,3,0,1] row_mask:0xf bank_mask:0xf bound_ctrl:1
	v_add_f32_dpp v161, v161, v161 quad_perm:[2,3,0,1] row_mask:0xf bank_mask:0xf bound_ctrl:1
	v_add_f32_dpp v172, v172, v172 row_half_mirror row_mask:0xf bank_mask:0xf bound_ctrl:1
	v_add_f32_dpp v174, v174, v174 row_half_mirror row_mask:0xf bank_mask:0xf bound_ctrl:1
	v_add_f32_dpp v160, v160, v160 row_half_mirror row_mask:0xf bank_mask:0xf bound_ctrl:1
	v_add_f32_dpp v161, v161, v161 row_half_mirror row_mask:0xf bank_mask:0xf bound_ctrl:1
	v_pk_fma_f32 v[72:73], v[32:33], v[172:173], v[218:219] op_sel_hi:[1,0,1]
	v_pk_fma_f32 v[80:81], v[32:33], v[174:175], v[226:227] op_sel_hi:[1,0,1]
	v_pk_fma_f32 v[74:75], v[34:35], v[172:173], v[220:221] op_sel_hi:[1,0,1]
	v_pk_fma_f32 v[82:83], v[34:35], v[174:175], v[228:229] op_sel_hi:[1,0,1]
	v_pk_fma_f32 v[76:77], v[36:37], v[172:173], v[222:223] op_sel_hi:[1,0,1]
	v_pk_fma_f32 v[84:85], v[36:37], v[174:175], v[230:231] op_sel_hi:[1,0,1]
	v_pk_fma_f32 v[78:79], v[38:39], v[172:173], v[224:225] op_sel_hi:[1,0,1]
	v_pk_fma_f32 v[86:87], v[38:39], v[174:175], v[234:235] op_sel_hi:[1,0,1]
	s_waitcnt lgkmcnt(0)
	v_pk_mul_f32 v[164:165], v[72:73], v[176:177]
	v_pk_mul_f32 v[166:167], v[80:81], v[176:177]
	ds_read_b128 v[208:211], v2 offset:18432
	v_pk_mul_f32 v[168:169], v[72:73], v[48:49]
	v_pk_mul_f32 v[170:171], v[80:81], v[48:49]
	ds_read_b128 v[212:215], v2 offset:18448
	v_pk_fma_f32 v[164:165], v[74:75], v[178:179], v[164:165]
	v_pk_fma_f32 v[166:167], v[82:83], v[178:179], v[166:167]
	ds_read_b128 v[4:7], v2 offset:6400
	v_pk_fma_f32 v[168:169], v[74:75], v[50:51], v[168:169]
	v_pk_fma_f32 v[170:171], v[82:83], v[50:51], v[170:171]
	ds_read_b128 v[8:11], v2 offset:6416
	v_pk_fma_f32 v[164:165], v[76:77], v[180:181], v[164:165]
	v_pk_fma_f32 v[166:167], v[84:85], v[180:181], v[166:167]
	ds_read_b128 v[40:43], v2 offset:14592
	v_pk_fma_f32 v[168:169], v[76:77], v[52:53], v[168:169]
	v_pk_fma_f32 v[170:171], v[84:85], v[52:53], v[170:171]
	ds_read_b128 v[44:47], v2 offset:14608
	v_pk_fma_f32 v[164:165], v[78:79], v[182:183], v[164:165]
	v_pk_fma_f32 v[166:167], v[86:87], v[182:183], v[166:167]
	ds_read_b64 v[26:27], v3 offset:43264
	v_pk_fma_f32 v[168:169], v[78:79], v[54:55], v[168:169]
	v_pk_fma_f32 v[170:171], v[86:87], v[54:55], v[170:171]
	ds_read_b128 v[12:15], v2 offset:2304
	v_pk_mul_f32 v[218:219], v[216:217], v[200:201] op_sel_hi:[0,1]
	v_pk_mul_f32 v[226:227], v[216:217], v[200:201] op_sel:[1,0]
	ds_read_b128 v[28:31], v2 offset:2320
	v_pk_mul_f32 v[220:221], v[216:217], v[202:203] op_sel_hi:[0,1]
	v_pk_mul_f32 v[228:229], v[216:217], v[202:203] op_sel:[1,0]
	ds_read_b128 v[32:35], v2 offset:10496
	v_pk_mul_f32 v[222:223], v[216:217], v[204:205] op_sel_hi:[0,1]
	v_pk_mul_f32 v[230:231], v[216:217], v[204:205] op_sel:[1,0]
	ds_read_b128 v[36:39], v2 offset:10512
	v_pk_mul_f32 v[224:225], v[216:217], v[206:207] op_sel_hi:[0,1]
	v_pk_mul_f32 v[234:235], v[216:217], v[206:207] op_sel:[1,0]
	v_add_f32_e32 v172, v164, v165
	v_add_f32_e32 v174, v166, v167
	v_add_f32_e32 v244, v168, v169
	v_add_f32_e32 v245, v170, v171
	v_pk_fma_f32 v[218:219], v[72:73], v[184:185], v[218:219]
	v_pk_fma_f32 v[226:227], v[80:81], v[184:185], v[226:227]
	v_pk_fma_f32 v[220:221], v[74:75], v[186:187], v[220:221]
	v_pk_fma_f32 v[228:229], v[82:83], v[186:187], v[228:229]
	v_add_f32_dpp v172, v172, v172 quad_perm:[1,0,3,2] row_mask:0xf bank_mask:0xf bound_ctrl:1
	v_add_f32_dpp v174, v174, v174 quad_perm:[1,0,3,2] row_mask:0xf bank_mask:0xf bound_ctrl:1
	v_add_f32_dpp v244, v244, v244 quad_perm:[1,0,3,2] row_mask:0xf bank_mask:0xf bound_ctrl:1
	v_add_f32_dpp v245, v245, v245 quad_perm:[1,0,3,2] row_mask:0xf bank_mask:0xf bound_ctrl:1
	v_pk_fma_f32 v[222:223], v[76:77], v[188:189], v[222:223]
	v_pk_fma_f32 v[230:231], v[84:85], v[188:189], v[230:231]
	v_pk_fma_f32 v[224:225], v[78:79], v[190:191], v[224:225]
	v_pk_fma_f32 v[234:235], v[86:87], v[190:191], v[234:235]
	v_add_f32_dpp v172, v172, v172 quad_perm:[2,3,0,1] row_mask:0xf bank_mask:0xf bound_ctrl:1
	v_add_f32_dpp v174, v174, v174 quad_perm:[2,3,0,1] row_mask:0xf bank_mask:0xf bound_ctrl:1
	v_add_f32_dpp v244, v244, v244 quad_perm:[2,3,0,1] row_mask:0xf bank_mask:0xf bound_ctrl:1
	v_add_f32_dpp v245, v245, v245 quad_perm:[2,3,0,1] row_mask:0xf bank_mask:0xf bound_ctrl:1
	v_add_f32_dpp v172, v172, v172 row_half_mirror row_mask:0xf bank_mask:0xf bound_ctrl:1
	v_add_f32_dpp v174, v174, v174 row_half_mirror row_mask:0xf bank_mask:0xf bound_ctrl:1
	v_add_f32_dpp v244, v244, v244 row_half_mirror row_mask:0xf bank_mask:0xf bound_ctrl:1
	v_add_f32_dpp v245, v245, v245 row_half_mirror row_mask:0xf bank_mask:0xf bound_ctrl:1
	v_pk_fma_f32 v[72:73], v[192:193], v[172:173], v[218:219] op_sel_hi:[1,0,1]
	v_pk_fma_f32 v[80:81], v[192:193], v[174:175], v[226:227] op_sel_hi:[1,0,1]
	v_pk_fma_f32 v[74:75], v[194:195], v[172:173], v[220:221] op_sel_hi:[1,0,1]
	v_pk_fma_f32 v[82:83], v[194:195], v[174:175], v[228:229] op_sel_hi:[1,0,1]
	v_pk_fma_f32 v[76:77], v[196:197], v[172:173], v[222:223] op_sel_hi:[1,0,1]
	v_pk_fma_f32 v[84:85], v[196:197], v[174:175], v[230:231] op_sel_hi:[1,0,1]
	v_pk_fma_f32 v[78:79], v[198:199], v[172:173], v[224:225] op_sel_hi:[1,0,1]
	v_pk_fma_f32 v[86:87], v[198:199], v[174:175], v[234:235] op_sel_hi:[1,0,1]
	ds_write2_b64 v246, v[160:161], v[244:245] offset0:192 offset1:224
	s_waitcnt lgkmcnt(1)
	v_pk_mul_f32 v[164:165], v[72:73], v[4:5]
	v_pk_mul_f32 v[166:167], v[80:81], v[4:5]
	ds_read_b128 v[48:51], v2 offset:18688
	v_pk_mul_f32 v[168:169], v[72:73], v[208:209]
	v_pk_mul_f32 v[170:171], v[80:81], v[208:209]
	ds_read_b128 v[52:55], v2 offset:18704
	v_pk_fma_f32 v[164:165], v[74:75], v[6:7], v[164:165]
	v_pk_fma_f32 v[166:167], v[82:83], v[6:7], v[166:167]
	ds_read_b128 v[176:179], v2 offset:6656
	v_pk_fma_f32 v[168:169], v[74:75], v[210:211], v[168:169]
	v_pk_fma_f32 v[170:171], v[82:83], v[210:211], v[170:171]
	ds_read_b128 v[180:183], v2 offset:6672
	v_pk_fma_f32 v[164:165], v[76:77], v[8:9], v[164:165]
	v_pk_fma_f32 v[166:167], v[84:85], v[8:9], v[166:167]
	ds_read_b128 v[200:203], v2 offset:14848
	v_pk_fma_f32 v[168:169], v[76:77], v[212:213], v[168:169]
	v_pk_fma_f32 v[170:171], v[84:85], v[212:213], v[170:171]
	ds_read_b128 v[204:207], v2 offset:14864
	v_pk_fma_f32 v[164:165], v[78:79], v[10:11], v[164:165]
	v_pk_fma_f32 v[166:167], v[86:87], v[10:11], v[166:167]
	ds_read_b64 v[216:217], v3 offset:43520
	v_pk_fma_f32 v[168:169], v[78:79], v[214:215], v[168:169]
	v_pk_fma_f32 v[170:171], v[86:87], v[214:215], v[170:171]
	ds_read_b128 v[184:187], v2 offset:2560
	v_pk_mul_f32 v[218:219], v[26:27], v[40:41] op_sel_hi:[0,1]
	v_pk_mul_f32 v[226:227], v[26:27], v[40:41] op_sel:[1,0]
	ds_read_b128 v[188:191], v2 offset:2576
	v_pk_mul_f32 v[220:221], v[26:27], v[42:43] op_sel_hi:[0,1]
	v_pk_mul_f32 v[228:229], v[26:27], v[42:43] op_sel:[1,0]
	ds_read_b128 v[192:195], v2 offset:10752
	v_pk_mul_f32 v[222:223], v[26:27], v[44:45] op_sel_hi:[0,1]
	v_pk_mul_f32 v[230:231], v[26:27], v[44:45] op_sel:[1,0]
	ds_read_b128 v[196:199], v2 offset:10768
	v_pk_mul_f32 v[224:225], v[26:27], v[46:47] op_sel_hi:[0,1]
	v_pk_mul_f32 v[234:235], v[26:27], v[46:47] op_sel:[1,0]
	v_add_f32_e32 v172, v164, v165
	v_add_f32_e32 v174, v166, v167
	v_add_f32_e32 v160, v168, v169
	v_add_f32_e32 v161, v170, v171
	v_pk_fma_f32 v[218:219], v[72:73], v[12:13], v[218:219]
	v_pk_fma_f32 v[226:227], v[80:81], v[12:13], v[226:227]
	v_pk_fma_f32 v[220:221], v[74:75], v[14:15], v[220:221]
	v_pk_fma_f32 v[228:229], v[82:83], v[14:15], v[228:229]
	v_add_f32_dpp v172, v172, v172 quad_perm:[1,0,3,2] row_mask:0xf bank_mask:0xf bound_ctrl:1
	v_add_f32_dpp v174, v174, v174 quad_perm:[1,0,3,2] row_mask:0xf bank_mask:0xf bound_ctrl:1
	v_add_f32_dpp v160, v160, v160 quad_perm:[1,0,3,2] row_mask:0xf bank_mask:0xf bound_ctrl:1
	v_add_f32_dpp v161, v161, v161 quad_perm:[1,0,3,2] row_mask:0xf bank_mask:0xf bound_ctrl:1
	v_pk_fma_f32 v[222:223], v[76:77], v[28:29], v[222:223]
	v_pk_fma_f32 v[230:231], v[84:85], v[28:29], v[230:231]
	v_pk_fma_f32 v[224:225], v[78:79], v[30:31], v[224:225]
	v_pk_fma_f32 v[234:235], v[86:87], v[30:31], v[234:235]
	v_add_f32_dpp v172, v172, v172 quad_perm:[2,3,0,1] row_mask:0xf bank_mask:0xf bound_ctrl:1
	v_add_f32_dpp v174, v174, v174 quad_perm:[2,3,0,1] row_mask:0xf bank_mask:0xf bound_ctrl:1
	v_add_f32_dpp v160, v160, v160 quad_perm:[2,3,0,1] row_mask:0xf bank_mask:0xf bound_ctrl:1
	v_add_f32_dpp v161, v161, v161 quad_perm:[2,3,0,1] row_mask:0xf bank_mask:0xf bound_ctrl:1
	v_add_f32_dpp v172, v172, v172 row_half_mirror row_mask:0xf bank_mask:0xf bound_ctrl:1
	v_add_f32_dpp v174, v174, v174 row_half_mirror row_mask:0xf bank_mask:0xf bound_ctrl:1
	v_add_f32_dpp v160, v160, v160 row_half_mirror row_mask:0xf bank_mask:0xf bound_ctrl:1
	v_add_f32_dpp v161, v161, v161 row_half_mirror row_mask:0xf bank_mask:0xf bound_ctrl:1
	v_pk_fma_f32 v[72:73], v[32:33], v[172:173], v[218:219] op_sel_hi:[1,0,1]
	v_pk_fma_f32 v[80:81], v[32:33], v[174:175], v[226:227] op_sel_hi:[1,0,1]
	v_pk_fma_f32 v[74:75], v[34:35], v[172:173], v[220:221] op_sel_hi:[1,0,1]
	v_pk_fma_f32 v[82:83], v[34:35], v[174:175], v[228:229] op_sel_hi:[1,0,1]
	v_pk_fma_f32 v[76:77], v[36:37], v[172:173], v[222:223] op_sel_hi:[1,0,1]
	v_pk_fma_f32 v[84:85], v[36:37], v[174:175], v[230:231] op_sel_hi:[1,0,1]
	v_pk_fma_f32 v[78:79], v[38:39], v[172:173], v[224:225] op_sel_hi:[1,0,1]
	v_pk_fma_f32 v[86:87], v[38:39], v[174:175], v[234:235] op_sel_hi:[1,0,1]
	s_waitcnt lgkmcnt(0)
	v_pk_mul_f32 v[164:165], v[72:73], v[176:177]
	v_pk_mul_f32 v[166:167], v[80:81], v[176:177]
	ds_read_b128 v[208:211], v2 offset:18944
	v_pk_mul_f32 v[168:169], v[72:73], v[48:49]
	v_pk_mul_f32 v[170:171], v[80:81], v[48:49]
	ds_read_b128 v[212:215], v2 offset:18960
	v_pk_fma_f32 v[164:165], v[74:75], v[178:179], v[164:165]
	v_pk_fma_f32 v[166:167], v[82:83], v[178:179], v[166:167]
	ds_read_b128 v[4:7], v2 offset:6912
	v_pk_fma_f32 v[168:169], v[74:75], v[50:51], v[168:169]
	v_pk_fma_f32 v[170:171], v[82:83], v[50:51], v[170:171]
	ds_read_b128 v[8:11], v2 offset:6928
	v_pk_fma_f32 v[164:165], v[76:77], v[180:181], v[164:165]
	v_pk_fma_f32 v[166:167], v[84:85], v[180:181], v[166:167]
	ds_read_b128 v[40:43], v2 offset:15104
	v_pk_fma_f32 v[168:169], v[76:77], v[52:53], v[168:169]
	v_pk_fma_f32 v[170:171], v[84:85], v[52:53], v[170:171]
	ds_read_b128 v[44:47], v2 offset:15120
	v_pk_fma_f32 v[164:165], v[78:79], v[182:183], v[164:165]
	v_pk_fma_f32 v[166:167], v[86:87], v[182:183], v[166:167]
	ds_read_b64 v[26:27], v3 offset:43776
	v_pk_fma_f32 v[168:169], v[78:79], v[54:55], v[168:169]
	v_pk_fma_f32 v[170:171], v[86:87], v[54:55], v[170:171]
	ds_read_b128 v[12:15], v2 offset:2816
	v_pk_mul_f32 v[218:219], v[216:217], v[200:201] op_sel_hi:[0,1]
	v_pk_mul_f32 v[226:227], v[216:217], v[200:201] op_sel:[1,0]
	ds_read_b128 v[28:31], v2 offset:2832
	v_pk_mul_f32 v[220:221], v[216:217], v[202:203] op_sel_hi:[0,1]
	v_pk_mul_f32 v[228:229], v[216:217], v[202:203] op_sel:[1,0]
	ds_read_b128 v[32:35], v2 offset:11008
	v_pk_mul_f32 v[222:223], v[216:217], v[204:205] op_sel_hi:[0,1]
	v_pk_mul_f32 v[230:231], v[216:217], v[204:205] op_sel:[1,0]
	ds_read_b128 v[36:39], v2 offset:11024
	v_pk_mul_f32 v[224:225], v[216:217], v[206:207] op_sel_hi:[0,1]
	v_pk_mul_f32 v[234:235], v[216:217], v[206:207] op_sel:[1,0]
	v_add_f32_e32 v172, v164, v165
	v_add_f32_e32 v174, v166, v167
	v_add_f32_e32 v244, v168, v169
	v_add_f32_e32 v245, v170, v171
	v_pk_fma_f32 v[218:219], v[72:73], v[184:185], v[218:219]
	v_pk_fma_f32 v[226:227], v[80:81], v[184:185], v[226:227]
	v_pk_fma_f32 v[220:221], v[74:75], v[186:187], v[220:221]
	v_pk_fma_f32 v[228:229], v[82:83], v[186:187], v[228:229]
	v_add_f32_dpp v172, v172, v172 quad_perm:[1,0,3,2] row_mask:0xf bank_mask:0xf bound_ctrl:1
	v_add_f32_dpp v174, v174, v174 quad_perm:[1,0,3,2] row_mask:0xf bank_mask:0xf bound_ctrl:1
	v_add_f32_dpp v244, v244, v244 quad_perm:[1,0,3,2] row_mask:0xf bank_mask:0xf bound_ctrl:1
	v_add_f32_dpp v245, v245, v245 quad_perm:[1,0,3,2] row_mask:0xf bank_mask:0xf bound_ctrl:1
	v_pk_fma_f32 v[222:223], v[76:77], v[188:189], v[222:223]
	v_pk_fma_f32 v[230:231], v[84:85], v[188:189], v[230:231]
	v_pk_fma_f32 v[224:225], v[78:79], v[190:191], v[224:225]
	v_pk_fma_f32 v[234:235], v[86:87], v[190:191], v[234:235]
	v_add_f32_dpp v172, v172, v172 quad_perm:[2,3,0,1] row_mask:0xf bank_mask:0xf bound_ctrl:1
	v_add_f32_dpp v174, v174, v174 quad_perm:[2,3,0,1] row_mask:0xf bank_mask:0xf bound_ctrl:1
	v_add_f32_dpp v244, v244, v244 quad_perm:[2,3,0,1] row_mask:0xf bank_mask:0xf bound_ctrl:1
	v_add_f32_dpp v245, v245, v245 quad_perm:[2,3,0,1] row_mask:0xf bank_mask:0xf bound_ctrl:1
	v_add_f32_dpp v172, v172, v172 row_half_mirror row_mask:0xf bank_mask:0xf bound_ctrl:1
	v_add_f32_dpp v174, v174, v174 row_half_mirror row_mask:0xf bank_mask:0xf bound_ctrl:1
	v_add_f32_dpp v244, v244, v244 row_half_mirror row_mask:0xf bank_mask:0xf bound_ctrl:1
	v_add_f32_dpp v245, v245, v245 row_half_mirror row_mask:0xf bank_mask:0xf bound_ctrl:1
	v_pk_fma_f32 v[72:73], v[192:193], v[172:173], v[218:219] op_sel_hi:[1,0,1]
	v_pk_fma_f32 v[80:81], v[192:193], v[174:175], v[226:227] op_sel_hi:[1,0,1]
	v_pk_fma_f32 v[74:75], v[194:195], v[172:173], v[220:221] op_sel_hi:[1,0,1]
	v_pk_fma_f32 v[82:83], v[194:195], v[174:175], v[228:229] op_sel_hi:[1,0,1]
	v_pk_fma_f32 v[76:77], v[196:197], v[172:173], v[222:223] op_sel_hi:[1,0,1]
	v_pk_fma_f32 v[84:85], v[196:197], v[174:175], v[230:231] op_sel_hi:[1,0,1]
	v_pk_fma_f32 v[78:79], v[198:199], v[172:173], v[224:225] op_sel_hi:[1,0,1]
	v_pk_fma_f32 v[86:87], v[198:199], v[174:175], v[234:235] op_sel_hi:[1,0,1]
	ds_write2_b64 v247, v[160:161], v[244:245] offset1:32
	s_waitcnt lgkmcnt(1)
	v_pk_mul_f32 v[164:165], v[72:73], v[4:5]
	v_pk_mul_f32 v[166:167], v[80:81], v[4:5]
	ds_read_b128 v[48:51], v2 offset:19200
	v_pk_mul_f32 v[168:169], v[72:73], v[208:209]
	v_pk_mul_f32 v[170:171], v[80:81], v[208:209]
	ds_read_b128 v[52:55], v2 offset:19216
	v_pk_fma_f32 v[164:165], v[74:75], v[6:7], v[164:165]
	v_pk_fma_f32 v[166:167], v[82:83], v[6:7], v[166:167]
	ds_read_b128 v[176:179], v2 offset:7168
	v_pk_fma_f32 v[168:169], v[74:75], v[210:211], v[168:169]
	v_pk_fma_f32 v[170:171], v[82:83], v[210:211], v[170:171]
	ds_read_b128 v[180:183], v2 offset:7184
	v_pk_fma_f32 v[164:165], v[76:77], v[8:9], v[164:165]
	v_pk_fma_f32 v[166:167], v[84:85], v[8:9], v[166:167]
	ds_read_b128 v[200:203], v2 offset:15360
	v_pk_fma_f32 v[168:169], v[76:77], v[212:213], v[168:169]
	v_pk_fma_f32 v[170:171], v[84:85], v[212:213], v[170:171]
	ds_read_b128 v[204:207], v2 offset:15376
	v_pk_fma_f32 v[164:165], v[78:79], v[10:11], v[164:165]
	v_pk_fma_f32 v[166:167], v[86:87], v[10:11], v[166:167]
	ds_read_b64 v[216:217], v3 offset:44032
	v_pk_fma_f32 v[168:169], v[78:79], v[214:215], v[168:169]
	v_pk_fma_f32 v[170:171], v[86:87], v[214:215], v[170:171]
	ds_read_b128 v[184:187], v2 offset:3072
	v_pk_mul_f32 v[218:219], v[26:27], v[40:41] op_sel_hi:[0,1]
	v_pk_mul_f32 v[226:227], v[26:27], v[40:41] op_sel:[1,0]
	ds_read_b128 v[188:191], v2 offset:3088
	v_pk_mul_f32 v[220:221], v[26:27], v[42:43] op_sel_hi:[0,1]
	v_pk_mul_f32 v[228:229], v[26:27], v[42:43] op_sel:[1,0]
	ds_read_b128 v[192:195], v2 offset:11264
	v_pk_mul_f32 v[222:223], v[26:27], v[44:45] op_sel_hi:[0,1]
	v_pk_mul_f32 v[230:231], v[26:27], v[44:45] op_sel:[1,0]
	ds_read_b128 v[196:199], v2 offset:11280
	v_pk_mul_f32 v[224:225], v[26:27], v[46:47] op_sel_hi:[0,1]
	v_pk_mul_f32 v[234:235], v[26:27], v[46:47] op_sel:[1,0]
	v_add_f32_e32 v172, v164, v165
	v_add_f32_e32 v174, v166, v167
	v_add_f32_e32 v160, v168, v169
	v_add_f32_e32 v161, v170, v171
	v_pk_fma_f32 v[218:219], v[72:73], v[12:13], v[218:219]
	v_pk_fma_f32 v[226:227], v[80:81], v[12:13], v[226:227]
	v_pk_fma_f32 v[220:221], v[74:75], v[14:15], v[220:221]
	v_pk_fma_f32 v[228:229], v[82:83], v[14:15], v[228:229]
	v_add_f32_dpp v172, v172, v172 quad_perm:[1,0,3,2] row_mask:0xf bank_mask:0xf bound_ctrl:1
	v_add_f32_dpp v174, v174, v174 quad_perm:[1,0,3,2] row_mask:0xf bank_mask:0xf bound_ctrl:1
	v_add_f32_dpp v160, v160, v160 quad_perm:[1,0,3,2] row_mask:0xf bank_mask:0xf bound_ctrl:1
	v_add_f32_dpp v161, v161, v161 quad_perm:[1,0,3,2] row_mask:0xf bank_mask:0xf bound_ctrl:1
	v_pk_fma_f32 v[222:223], v[76:77], v[28:29], v[222:223]
	v_pk_fma_f32 v[230:231], v[84:85], v[28:29], v[230:231]
	v_pk_fma_f32 v[224:225], v[78:79], v[30:31], v[224:225]
	v_pk_fma_f32 v[234:235], v[86:87], v[30:31], v[234:235]
	v_add_f32_dpp v172, v172, v172 quad_perm:[2,3,0,1] row_mask:0xf bank_mask:0xf bound_ctrl:1
	v_add_f32_dpp v174, v174, v174 quad_perm:[2,3,0,1] row_mask:0xf bank_mask:0xf bound_ctrl:1
	v_add_f32_dpp v160, v160, v160 quad_perm:[2,3,0,1] row_mask:0xf bank_mask:0xf bound_ctrl:1
	v_add_f32_dpp v161, v161, v161 quad_perm:[2,3,0,1] row_mask:0xf bank_mask:0xf bound_ctrl:1
	v_add_f32_dpp v172, v172, v172 row_half_mirror row_mask:0xf bank_mask:0xf bound_ctrl:1
	v_add_f32_dpp v174, v174, v174 row_half_mirror row_mask:0xf bank_mask:0xf bound_ctrl:1
	v_add_f32_dpp v160, v160, v160 row_half_mirror row_mask:0xf bank_mask:0xf bound_ctrl:1
	v_add_f32_dpp v161, v161, v161 row_half_mirror row_mask:0xf bank_mask:0xf bound_ctrl:1
	v_pk_fma_f32 v[72:73], v[32:33], v[172:173], v[218:219] op_sel_hi:[1,0,1]
	v_pk_fma_f32 v[80:81], v[32:33], v[174:175], v[226:227] op_sel_hi:[1,0,1]
	v_pk_fma_f32 v[74:75], v[34:35], v[172:173], v[220:221] op_sel_hi:[1,0,1]
	v_pk_fma_f32 v[82:83], v[34:35], v[174:175], v[228:229] op_sel_hi:[1,0,1]
	v_pk_fma_f32 v[76:77], v[36:37], v[172:173], v[222:223] op_sel_hi:[1,0,1]
	v_pk_fma_f32 v[84:85], v[36:37], v[174:175], v[230:231] op_sel_hi:[1,0,1]
	v_pk_fma_f32 v[78:79], v[38:39], v[172:173], v[224:225] op_sel_hi:[1,0,1]
	v_pk_fma_f32 v[86:87], v[38:39], v[174:175], v[234:235] op_sel_hi:[1,0,1]
	s_waitcnt lgkmcnt(0)
	v_pk_mul_f32 v[164:165], v[72:73], v[176:177]
	v_pk_mul_f32 v[166:167], v[80:81], v[176:177]
	ds_read_b128 v[208:211], v2 offset:19456
	v_pk_mul_f32 v[168:169], v[72:73], v[48:49]
	v_pk_mul_f32 v[170:171], v[80:81], v[48:49]
	ds_read_b128 v[212:215], v2 offset:19472
	v_pk_fma_f32 v[164:165], v[74:75], v[178:179], v[164:165]
	v_pk_fma_f32 v[166:167], v[82:83], v[178:179], v[166:167]
	ds_read_b128 v[4:7], v2 offset:7424
	v_pk_fma_f32 v[168:169], v[74:75], v[50:51], v[168:169]
	v_pk_fma_f32 v[170:171], v[82:83], v[50:51], v[170:171]
	ds_read_b128 v[8:11], v2 offset:7440
	v_pk_fma_f32 v[164:165], v[76:77], v[180:181], v[164:165]
	v_pk_fma_f32 v[166:167], v[84:85], v[180:181], v[166:167]
	ds_read_b128 v[40:43], v2 offset:15616
	v_pk_fma_f32 v[168:169], v[76:77], v[52:53], v[168:169]
	v_pk_fma_f32 v[170:171], v[84:85], v[52:53], v[170:171]
	ds_read_b128 v[44:47], v2 offset:15632
	v_pk_fma_f32 v[164:165], v[78:79], v[182:183], v[164:165]
	v_pk_fma_f32 v[166:167], v[86:87], v[182:183], v[166:167]
	ds_read_b64 v[26:27], v3 offset:44288
	v_pk_fma_f32 v[168:169], v[78:79], v[54:55], v[168:169]
	v_pk_fma_f32 v[170:171], v[86:87], v[54:55], v[170:171]
	ds_read_b128 v[12:15], v2 offset:3328
	v_pk_mul_f32 v[218:219], v[216:217], v[200:201] op_sel_hi:[0,1]
	v_pk_mul_f32 v[226:227], v[216:217], v[200:201] op_sel:[1,0]
	ds_read_b128 v[28:31], v2 offset:3344
	v_pk_mul_f32 v[220:221], v[216:217], v[202:203] op_sel_hi:[0,1]
	v_pk_mul_f32 v[228:229], v[216:217], v[202:203] op_sel:[1,0]
	ds_read_b128 v[32:35], v2 offset:11520
	v_pk_mul_f32 v[222:223], v[216:217], v[204:205] op_sel_hi:[0,1]
	v_pk_mul_f32 v[230:231], v[216:217], v[204:205] op_sel:[1,0]
	ds_read_b128 v[36:39], v2 offset:11536
	v_pk_mul_f32 v[224:225], v[216:217], v[206:207] op_sel_hi:[0,1]
	v_pk_mul_f32 v[234:235], v[216:217], v[206:207] op_sel:[1,0]
	v_add_f32_e32 v172, v164, v165
	v_add_f32_e32 v174, v166, v167
	v_add_f32_e32 v244, v168, v169
	v_add_f32_e32 v245, v170, v171
	v_pk_fma_f32 v[218:219], v[72:73], v[184:185], v[218:219]
	v_pk_fma_f32 v[226:227], v[80:81], v[184:185], v[226:227]
	v_pk_fma_f32 v[220:221], v[74:75], v[186:187], v[220:221]
	v_pk_fma_f32 v[228:229], v[82:83], v[186:187], v[228:229]
	v_add_f32_dpp v172, v172, v172 quad_perm:[1,0,3,2] row_mask:0xf bank_mask:0xf bound_ctrl:1
	v_add_f32_dpp v174, v174, v174 quad_perm:[1,0,3,2] row_mask:0xf bank_mask:0xf bound_ctrl:1
	v_add_f32_dpp v244, v244, v244 quad_perm:[1,0,3,2] row_mask:0xf bank_mask:0xf bound_ctrl:1
	v_add_f32_dpp v245, v245, v245 quad_perm:[1,0,3,2] row_mask:0xf bank_mask:0xf bound_ctrl:1
	v_pk_fma_f32 v[222:223], v[76:77], v[188:189], v[222:223]
	v_pk_fma_f32 v[230:231], v[84:85], v[188:189], v[230:231]
	v_pk_fma_f32 v[224:225], v[78:79], v[190:191], v[224:225]
	v_pk_fma_f32 v[234:235], v[86:87], v[190:191], v[234:235]
	v_add_f32_dpp v172, v172, v172 quad_perm:[2,3,0,1] row_mask:0xf bank_mask:0xf bound_ctrl:1
	v_add_f32_dpp v174, v174, v174 quad_perm:[2,3,0,1] row_mask:0xf bank_mask:0xf bound_ctrl:1
	v_add_f32_dpp v244, v244, v244 quad_perm:[2,3,0,1] row_mask:0xf bank_mask:0xf bound_ctrl:1
	v_add_f32_dpp v245, v245, v245 quad_perm:[2,3,0,1] row_mask:0xf bank_mask:0xf bound_ctrl:1
	v_add_f32_dpp v172, v172, v172 row_half_mirror row_mask:0xf bank_mask:0xf bound_ctrl:1
	v_add_f32_dpp v174, v174, v174 row_half_mirror row_mask:0xf bank_mask:0xf bound_ctrl:1
	v_add_f32_dpp v244, v244, v244 row_half_mirror row_mask:0xf bank_mask:0xf bound_ctrl:1
	v_add_f32_dpp v245, v245, v245 row_half_mirror row_mask:0xf bank_mask:0xf bound_ctrl:1
	v_pk_fma_f32 v[72:73], v[192:193], v[172:173], v[218:219] op_sel_hi:[1,0,1]
	v_pk_fma_f32 v[80:81], v[192:193], v[174:175], v[226:227] op_sel_hi:[1,0,1]
	v_pk_fma_f32 v[74:75], v[194:195], v[172:173], v[220:221] op_sel_hi:[1,0,1]
	v_pk_fma_f32 v[82:83], v[194:195], v[174:175], v[228:229] op_sel_hi:[1,0,1]
	v_pk_fma_f32 v[76:77], v[196:197], v[172:173], v[222:223] op_sel_hi:[1,0,1]
	v_pk_fma_f32 v[84:85], v[196:197], v[174:175], v[230:231] op_sel_hi:[1,0,1]
	v_pk_fma_f32 v[78:79], v[198:199], v[172:173], v[224:225] op_sel_hi:[1,0,1]
	v_pk_fma_f32 v[86:87], v[198:199], v[174:175], v[234:235] op_sel_hi:[1,0,1]
	ds_write2_b64 v247, v[160:161], v[244:245] offset0:64 offset1:96
	s_waitcnt lgkmcnt(1)
	v_pk_mul_f32 v[164:165], v[72:73], v[4:5]
	v_pk_mul_f32 v[166:167], v[80:81], v[4:5]
	ds_read_b128 v[48:51], v2 offset:19712
	v_pk_mul_f32 v[168:169], v[72:73], v[208:209]
	v_pk_mul_f32 v[170:171], v[80:81], v[208:209]
	ds_read_b128 v[52:55], v2 offset:19728
	v_pk_fma_f32 v[164:165], v[74:75], v[6:7], v[164:165]
	v_pk_fma_f32 v[166:167], v[82:83], v[6:7], v[166:167]
	ds_read_b128 v[176:179], v2 offset:7680
	v_pk_fma_f32 v[168:169], v[74:75], v[210:211], v[168:169]
	v_pk_fma_f32 v[170:171], v[82:83], v[210:211], v[170:171]
	ds_read_b128 v[180:183], v2 offset:7696
	v_pk_fma_f32 v[164:165], v[76:77], v[8:9], v[164:165]
	v_pk_fma_f32 v[166:167], v[84:85], v[8:9], v[166:167]
	ds_read_b128 v[200:203], v2 offset:15872
	v_pk_fma_f32 v[168:169], v[76:77], v[212:213], v[168:169]
	v_pk_fma_f32 v[170:171], v[84:85], v[212:213], v[170:171]
	ds_read_b128 v[204:207], v2 offset:15888
	v_pk_fma_f32 v[164:165], v[78:79], v[10:11], v[164:165]
	v_pk_fma_f32 v[166:167], v[86:87], v[10:11], v[166:167]
	ds_read_b64 v[216:217], v3 offset:44544
	v_pk_fma_f32 v[168:169], v[78:79], v[214:215], v[168:169]
	v_pk_fma_f32 v[170:171], v[86:87], v[214:215], v[170:171]
	ds_read_b128 v[184:187], v2 offset:3584
	v_pk_mul_f32 v[218:219], v[26:27], v[40:41] op_sel_hi:[0,1]
	v_pk_mul_f32 v[226:227], v[26:27], v[40:41] op_sel:[1,0]
	ds_read_b128 v[188:191], v2 offset:3600
	v_pk_mul_f32 v[220:221], v[26:27], v[42:43] op_sel_hi:[0,1]
	v_pk_mul_f32 v[228:229], v[26:27], v[42:43] op_sel:[1,0]
	ds_read_b128 v[192:195], v2 offset:11776
	v_pk_mul_f32 v[222:223], v[26:27], v[44:45] op_sel_hi:[0,1]
	v_pk_mul_f32 v[230:231], v[26:27], v[44:45] op_sel:[1,0]
	ds_read_b128 v[196:199], v2 offset:11792
	v_pk_mul_f32 v[224:225], v[26:27], v[46:47] op_sel_hi:[0,1]
	v_pk_mul_f32 v[234:235], v[26:27], v[46:47] op_sel:[1,0]
	v_add_f32_e32 v172, v164, v165
	v_add_f32_e32 v174, v166, v167
	v_add_f32_e32 v160, v168, v169
	v_add_f32_e32 v161, v170, v171
	v_pk_fma_f32 v[218:219], v[72:73], v[12:13], v[218:219]
	v_pk_fma_f32 v[226:227], v[80:81], v[12:13], v[226:227]
	v_pk_fma_f32 v[220:221], v[74:75], v[14:15], v[220:221]
	v_pk_fma_f32 v[228:229], v[82:83], v[14:15], v[228:229]
	v_add_f32_dpp v172, v172, v172 quad_perm:[1,0,3,2] row_mask:0xf bank_mask:0xf bound_ctrl:1
	v_add_f32_dpp v174, v174, v174 quad_perm:[1,0,3,2] row_mask:0xf bank_mask:0xf bound_ctrl:1
	v_add_f32_dpp v160, v160, v160 quad_perm:[1,0,3,2] row_mask:0xf bank_mask:0xf bound_ctrl:1
	v_add_f32_dpp v161, v161, v161 quad_perm:[1,0,3,2] row_mask:0xf bank_mask:0xf bound_ctrl:1
	v_pk_fma_f32 v[222:223], v[76:77], v[28:29], v[222:223]
	v_pk_fma_f32 v[230:231], v[84:85], v[28:29], v[230:231]
	v_pk_fma_f32 v[224:225], v[78:79], v[30:31], v[224:225]
	v_pk_fma_f32 v[234:235], v[86:87], v[30:31], v[234:235]
	v_add_f32_dpp v172, v172, v172 quad_perm:[2,3,0,1] row_mask:0xf bank_mask:0xf bound_ctrl:1
	v_add_f32_dpp v174, v174, v174 quad_perm:[2,3,0,1] row_mask:0xf bank_mask:0xf bound_ctrl:1
	v_add_f32_dpp v160, v160, v160 quad_perm:[2,3,0,1] row_mask:0xf bank_mask:0xf bound_ctrl:1
	v_add_f32_dpp v161, v161, v161 quad_perm:[2,3,0,1] row_mask:0xf bank_mask:0xf bound_ctrl:1
	v_add_f32_dpp v172, v172, v172 row_half_mirror row_mask:0xf bank_mask:0xf bound_ctrl:1
	v_add_f32_dpp v174, v174, v174 row_half_mirror row_mask:0xf bank_mask:0xf bound_ctrl:1
	v_add_f32_dpp v160, v160, v160 row_half_mirror row_mask:0xf bank_mask:0xf bound_ctrl:1
	v_add_f32_dpp v161, v161, v161 row_half_mirror row_mask:0xf bank_mask:0xf bound_ctrl:1
	v_pk_fma_f32 v[72:73], v[32:33], v[172:173], v[218:219] op_sel_hi:[1,0,1]
	v_pk_fma_f32 v[80:81], v[32:33], v[174:175], v[226:227] op_sel_hi:[1,0,1]
	v_pk_fma_f32 v[74:75], v[34:35], v[172:173], v[220:221] op_sel_hi:[1,0,1]
	v_pk_fma_f32 v[82:83], v[34:35], v[174:175], v[228:229] op_sel_hi:[1,0,1]
	v_pk_fma_f32 v[76:77], v[36:37], v[172:173], v[222:223] op_sel_hi:[1,0,1]
	v_pk_fma_f32 v[84:85], v[36:37], v[174:175], v[230:231] op_sel_hi:[1,0,1]
	v_pk_fma_f32 v[78:79], v[38:39], v[172:173], v[224:225] op_sel_hi:[1,0,1]
	v_pk_fma_f32 v[86:87], v[38:39], v[174:175], v[234:235] op_sel_hi:[1,0,1]
	s_waitcnt lgkmcnt(0)
	v_pk_mul_f32 v[164:165], v[72:73], v[176:177]
	v_pk_mul_f32 v[166:167], v[80:81], v[176:177]
	ds_read_b128 v[208:211], v2 offset:19968
	v_pk_mul_f32 v[168:169], v[72:73], v[48:49]
	v_pk_mul_f32 v[170:171], v[80:81], v[48:49]
	ds_read_b128 v[212:215], v2 offset:19984
	v_pk_fma_f32 v[164:165], v[74:75], v[178:179], v[164:165]
	v_pk_fma_f32 v[166:167], v[82:83], v[178:179], v[166:167]
	ds_read_b128 v[4:7], v2 offset:7936
	v_pk_fma_f32 v[168:169], v[74:75], v[50:51], v[168:169]
	v_pk_fma_f32 v[170:171], v[82:83], v[50:51], v[170:171]
	ds_read_b128 v[8:11], v2 offset:7952
	v_pk_fma_f32 v[164:165], v[76:77], v[180:181], v[164:165]
	v_pk_fma_f32 v[166:167], v[84:85], v[180:181], v[166:167]
	ds_read_b128 v[40:43], v2 offset:16128
	v_pk_fma_f32 v[168:169], v[76:77], v[52:53], v[168:169]
	v_pk_fma_f32 v[170:171], v[84:85], v[52:53], v[170:171]
	ds_read_b128 v[44:47], v2 offset:16144
	v_pk_fma_f32 v[164:165], v[78:79], v[182:183], v[164:165]
	v_pk_fma_f32 v[166:167], v[86:87], v[182:183], v[166:167]
	ds_read_b64 v[26:27], v3 offset:44800
	v_pk_fma_f32 v[168:169], v[78:79], v[54:55], v[168:169]
	v_pk_fma_f32 v[170:171], v[86:87], v[54:55], v[170:171]
	ds_read_b128 v[12:15], v2 offset:3840
	v_pk_mul_f32 v[218:219], v[216:217], v[200:201] op_sel_hi:[0,1]
	v_pk_mul_f32 v[226:227], v[216:217], v[200:201] op_sel:[1,0]
	ds_read_b128 v[28:31], v2 offset:3856
	v_pk_mul_f32 v[220:221], v[216:217], v[202:203] op_sel_hi:[0,1]
	v_pk_mul_f32 v[228:229], v[216:217], v[202:203] op_sel:[1,0]
	ds_read_b128 v[32:35], v2 offset:12032
	v_pk_mul_f32 v[222:223], v[216:217], v[204:205] op_sel_hi:[0,1]
	v_pk_mul_f32 v[230:231], v[216:217], v[204:205] op_sel:[1,0]
	ds_read_b128 v[36:39], v2 offset:12048
	v_pk_mul_f32 v[224:225], v[216:217], v[206:207] op_sel_hi:[0,1]
	v_pk_mul_f32 v[234:235], v[216:217], v[206:207] op_sel:[1,0]
	v_add_f32_e32 v172, v164, v165
	v_add_f32_e32 v174, v166, v167
	v_add_f32_e32 v244, v168, v169
	v_add_f32_e32 v245, v170, v171
	v_pk_fma_f32 v[218:219], v[72:73], v[184:185], v[218:219]
	v_pk_fma_f32 v[226:227], v[80:81], v[184:185], v[226:227]
	v_pk_fma_f32 v[220:221], v[74:75], v[186:187], v[220:221]
	v_pk_fma_f32 v[228:229], v[82:83], v[186:187], v[228:229]
	v_add_f32_dpp v172, v172, v172 quad_perm:[1,0,3,2] row_mask:0xf bank_mask:0xf bound_ctrl:1
	v_add_f32_dpp v174, v174, v174 quad_perm:[1,0,3,2] row_mask:0xf bank_mask:0xf bound_ctrl:1
	v_add_f32_dpp v244, v244, v244 quad_perm:[1,0,3,2] row_mask:0xf bank_mask:0xf bound_ctrl:1
	v_add_f32_dpp v245, v245, v245 quad_perm:[1,0,3,2] row_mask:0xf bank_mask:0xf bound_ctrl:1
	v_pk_fma_f32 v[222:223], v[76:77], v[188:189], v[222:223]
	v_pk_fma_f32 v[230:231], v[84:85], v[188:189], v[230:231]
	v_pk_fma_f32 v[224:225], v[78:79], v[190:191], v[224:225]
	v_pk_fma_f32 v[234:235], v[86:87], v[190:191], v[234:235]
	v_add_f32_dpp v172, v172, v172 quad_perm:[2,3,0,1] row_mask:0xf bank_mask:0xf bound_ctrl:1
	v_add_f32_dpp v174, v174, v174 quad_perm:[2,3,0,1] row_mask:0xf bank_mask:0xf bound_ctrl:1
	v_add_f32_dpp v244, v244, v244 quad_perm:[2,3,0,1] row_mask:0xf bank_mask:0xf bound_ctrl:1
	v_add_f32_dpp v245, v245, v245 quad_perm:[2,3,0,1] row_mask:0xf bank_mask:0xf bound_ctrl:1
	v_add_f32_dpp v172, v172, v172 row_half_mirror row_mask:0xf bank_mask:0xf bound_ctrl:1
	v_add_f32_dpp v174, v174, v174 row_half_mirror row_mask:0xf bank_mask:0xf bound_ctrl:1
	v_add_f32_dpp v244, v244, v244 row_half_mirror row_mask:0xf bank_mask:0xf bound_ctrl:1
	v_add_f32_dpp v245, v245, v245 row_half_mirror row_mask:0xf bank_mask:0xf bound_ctrl:1
	v_pk_fma_f32 v[72:73], v[192:193], v[172:173], v[218:219] op_sel_hi:[1,0,1]
	v_pk_fma_f32 v[80:81], v[192:193], v[174:175], v[226:227] op_sel_hi:[1,0,1]
	v_pk_fma_f32 v[74:75], v[194:195], v[172:173], v[220:221] op_sel_hi:[1,0,1]
	v_pk_fma_f32 v[82:83], v[194:195], v[174:175], v[228:229] op_sel_hi:[1,0,1]
	v_pk_fma_f32 v[76:77], v[196:197], v[172:173], v[222:223] op_sel_hi:[1,0,1]
	v_pk_fma_f32 v[84:85], v[196:197], v[174:175], v[230:231] op_sel_hi:[1,0,1]
	v_pk_fma_f32 v[78:79], v[198:199], v[172:173], v[224:225] op_sel_hi:[1,0,1]
	v_pk_fma_f32 v[86:87], v[198:199], v[174:175], v[234:235] op_sel_hi:[1,0,1]
	ds_write2_b64 v247, v[160:161], v[244:245] offset0:128 offset1:160
	s_waitcnt lgkmcnt(1)
	v_pk_mul_f32 v[164:165], v[72:73], v[4:5]
	v_pk_mul_f32 v[166:167], v[80:81], v[4:5]
	ds_read_b128 v[48:51], v2 offset:20224
	v_pk_mul_f32 v[168:169], v[72:73], v[208:209]
	v_pk_mul_f32 v[170:171], v[80:81], v[208:209]
	ds_read_b128 v[52:55], v2 offset:20240
	v_pk_fma_f32 v[164:165], v[74:75], v[6:7], v[164:165]
	v_pk_fma_f32 v[166:167], v[82:83], v[6:7], v[166:167]
	v_pk_fma_f32 v[168:169], v[74:75], v[210:211], v[168:169]
	v_pk_fma_f32 v[170:171], v[82:83], v[210:211], v[170:171]
	v_pk_fma_f32 v[164:165], v[76:77], v[8:9], v[164:165]
	v_pk_fma_f32 v[166:167], v[84:85], v[8:9], v[166:167]
	v_pk_fma_f32 v[168:169], v[76:77], v[212:213], v[168:169]
	v_pk_fma_f32 v[170:171], v[84:85], v[212:213], v[170:171]
	v_pk_fma_f32 v[164:165], v[78:79], v[10:11], v[164:165]
	v_pk_fma_f32 v[166:167], v[86:87], v[10:11], v[166:167]
	v_pk_fma_f32 v[168:169], v[78:79], v[214:215], v[168:169]
	v_pk_fma_f32 v[170:171], v[86:87], v[214:215], v[170:171]
	v_pk_mul_f32 v[218:219], v[26:27], v[40:41] op_sel_hi:[0,1]
	v_pk_mul_f32 v[226:227], v[26:27], v[40:41] op_sel:[1,0]
	v_pk_mul_f32 v[220:221], v[26:27], v[42:43] op_sel_hi:[0,1]
	v_pk_mul_f32 v[228:229], v[26:27], v[42:43] op_sel:[1,0]
	v_pk_mul_f32 v[222:223], v[26:27], v[44:45] op_sel_hi:[0,1]
	v_pk_mul_f32 v[230:231], v[26:27], v[44:45] op_sel:[1,0]
	v_pk_mul_f32 v[224:225], v[26:27], v[46:47] op_sel_hi:[0,1]
	v_pk_mul_f32 v[234:235], v[26:27], v[46:47] op_sel:[1,0]
	v_add_f32_e32 v172, v164, v165
	v_add_f32_e32 v174, v166, v167
	v_add_f32_e32 v160, v168, v169
	v_add_f32_e32 v161, v170, v171
	v_pk_fma_f32 v[218:219], v[72:73], v[12:13], v[218:219]
	v_pk_fma_f32 v[226:227], v[80:81], v[12:13], v[226:227]
	v_pk_fma_f32 v[220:221], v[74:75], v[14:15], v[220:221]
	v_pk_fma_f32 v[228:229], v[82:83], v[14:15], v[228:229]
	v_add_f32_dpp v172, v172, v172 quad_perm:[1,0,3,2] row_mask:0xf bank_mask:0xf bound_ctrl:1
	v_add_f32_dpp v174, v174, v174 quad_perm:[1,0,3,2] row_mask:0xf bank_mask:0xf bound_ctrl:1
	v_add_f32_dpp v160, v160, v160 quad_perm:[1,0,3,2] row_mask:0xf bank_mask:0xf bound_ctrl:1
	v_add_f32_dpp v161, v161, v161 quad_perm:[1,0,3,2] row_mask:0xf bank_mask:0xf bound_ctrl:1
	v_pk_fma_f32 v[222:223], v[76:77], v[28:29], v[222:223]
	v_pk_fma_f32 v[230:231], v[84:85], v[28:29], v[230:231]
	v_pk_fma_f32 v[224:225], v[78:79], v[30:31], v[224:225]
	v_pk_fma_f32 v[234:235], v[86:87], v[30:31], v[234:235]
	v_add_f32_dpp v172, v172, v172 quad_perm:[2,3,0,1] row_mask:0xf bank_mask:0xf bound_ctrl:1
	v_add_f32_dpp v174, v174, v174 quad_perm:[2,3,0,1] row_mask:0xf bank_mask:0xf bound_ctrl:1
	v_add_f32_dpp v160, v160, v160 quad_perm:[2,3,0,1] row_mask:0xf bank_mask:0xf bound_ctrl:1
	v_add_f32_dpp v161, v161, v161 quad_perm:[2,3,0,1] row_mask:0xf bank_mask:0xf bound_ctrl:1
	v_add_f32_dpp v172, v172, v172 row_half_mirror row_mask:0xf bank_mask:0xf bound_ctrl:1
	v_add_f32_dpp v174, v174, v174 row_half_mirror row_mask:0xf bank_mask:0xf bound_ctrl:1
	v_add_f32_dpp v160, v160, v160 row_half_mirror row_mask:0xf bank_mask:0xf bound_ctrl:1
	v_add_f32_dpp v161, v161, v161 row_half_mirror row_mask:0xf bank_mask:0xf bound_ctrl:1
	v_pk_fma_f32 v[72:73], v[32:33], v[172:173], v[218:219] op_sel_hi:[1,0,1]
	v_pk_fma_f32 v[80:81], v[32:33], v[174:175], v[226:227] op_sel_hi:[1,0,1]
	v_pk_fma_f32 v[74:75], v[34:35], v[172:173], v[220:221] op_sel_hi:[1,0,1]
	v_pk_fma_f32 v[82:83], v[34:35], v[174:175], v[228:229] op_sel_hi:[1,0,1]
	v_pk_fma_f32 v[76:77], v[36:37], v[172:173], v[222:223] op_sel_hi:[1,0,1]
	v_pk_fma_f32 v[84:85], v[36:37], v[174:175], v[230:231] op_sel_hi:[1,0,1]
	v_pk_fma_f32 v[78:79], v[38:39], v[172:173], v[224:225] op_sel_hi:[1,0,1]
	v_pk_fma_f32 v[86:87], v[38:39], v[174:175], v[234:235] op_sel_hi:[1,0,1]
	s_waitcnt lgkmcnt(1)
	v_pk_mul_f32 v[168:169], v[72:73], v[48:49]
	v_pk_mul_f32 v[170:171], v[80:81], v[48:49]
	v_pk_fma_f32 v[168:169], v[74:75], v[50:51], v[168:169]
	v_pk_fma_f32 v[170:171], v[82:83], v[50:51], v[170:171]
	s_waitcnt lgkmcnt(0)
	v_pk_fma_f32 v[168:169], v[76:77], v[52:53], v[168:169]
	v_pk_fma_f32 v[170:171], v[84:85], v[52:53], v[170:171]
	v_pk_fma_f32 v[168:169], v[78:79], v[54:55], v[168:169]
	v_pk_fma_f32 v[170:171], v[86:87], v[54:55], v[170:171]
	v_add_f32_e32 v244, v168, v169
	v_add_f32_e32 v245, v170, v171
	s_nop 0
	v_add_f32_dpp v244, v244, v244 quad_perm:[1,0,3,2] row_mask:0xf bank_mask:0xf bound_ctrl:1
	v_add_f32_dpp v245, v245, v245 quad_perm:[1,0,3,2] row_mask:0xf bank_mask:0xf bound_ctrl:1
	s_nop 0
	v_add_f32_dpp v244, v244, v244 quad_perm:[2,3,0,1] row_mask:0xf bank_mask:0xf bound_ctrl:1
	v_add_f32_dpp v245, v245, v245 quad_perm:[2,3,0,1] row_mask:0xf bank_mask:0xf bound_ctrl:1
	s_nop 0
	v_add_f32_dpp v244, v244, v244 row_half_mirror row_mask:0xf bank_mask:0xf bound_ctrl:1
	v_add_f32_dpp v245, v245, v245 row_half_mirror row_mask:0xf bank_mask:0xf bound_ctrl:1
	ds_write2_b64 v247, v[160:161], v[244:245] offset0:192 offset1:224
	s_add_i32 s3, s2, 1
	s_mov_b64 s[36:37], 0
